# P1 shift-image tasks: dwordx2 rolling prefetch (64 loads in flight, pair-lane transposition), runtime row stride; same MFMA order
# baseline (speedup 1.0000x reference)
.LBB0_133:
	s_waitcnt vmcnt(0)
	s_mov_b32 vcc_lo, 0xaaaaaaaa
	s_mov_b32 vcc_hi, 0xaaaaaaaa
	v_readfirstlane_b32 s100, v20
	v_readfirstlane_b32 s101, v21
	v_and_b32_e32 v201, 1, v227
	v_lshrrev_b32_e32 v202, 4, v227
	v_lshl_add_u32 v202, v202, 3, v201
	v_mul_lo_u32 v86, v202, s40
	v_and_b32_e32 v201, 14, v227
	v_lshl_add_u32 v86, v201, 2, v86
	v_add_u32_e32 v87, v23, v22
	v_add_u32_e32 v88, 0x11220, v87
	v_add_u32_e32 v89, v24, v22
	v_add_u32_e32 v200, 0x11220, v89
	ds_read_b128 v[164:167], v87
	ds_read_b128 v[168:171], v88
	ds_read_b128 v[172:175], v87 offset:33024
	ds_read_b128 v[176:179], v88 offset:33024
	ds_read_b128 v[180:183], v89
	ds_read_b128 v[184:187], v200
	global_load_dwordx2 v[26:27], v86, s[100:101]
	s_lshl_b32 s4, s40, 1
	s_add_u32 s100, s100, s4
	s_addc_u32 s101, s101, 0
	global_load_dwordx2 v[28:29], v86, s[100:101]
	s_lshl_b32 s4, s40, 1
	s_add_u32 s100, s100, s4
	s_addc_u32 s101, s101, 0
	global_load_dwordx2 v[30:31], v86, s[100:101]
	s_lshl_b32 s4, s40, 1
	s_add_u32 s100, s100, s4
	s_addc_u32 s101, s101, 0
	global_load_dwordx2 v[32:33], v86, s[100:101]
	s_mul_i32 s4, s40, 26
	s_add_u32 s100, s100, s4
	s_addc_u32 s101, s101, 0
	global_load_dwordx2 v[34:35], v86, s[100:101]
	s_lshl_b32 s4, s40, 1
	s_add_u32 s100, s100, s4
	s_addc_u32 s101, s101, 0
	global_load_dwordx2 v[36:37], v86, s[100:101]
	s_lshl_b32 s4, s40, 1
	s_add_u32 s100, s100, s4
	s_addc_u32 s101, s101, 0
	global_load_dwordx2 v[38:39], v86, s[100:101]
	s_lshl_b32 s4, s40, 1
	s_add_u32 s100, s100, s4
	s_addc_u32 s101, s101, 0
	global_load_dwordx2 v[40:41], v86, s[100:101]
	s_mul_i32 s4, s40, 26
	s_add_u32 s100, s100, s4
	s_addc_u32 s101, s101, 0
	global_load_dwordx2 v[42:43], v86, s[100:101]
	s_lshl_b32 s4, s40, 1
	s_add_u32 s100, s100, s4
	s_addc_u32 s101, s101, 0
	global_load_dwordx2 v[44:45], v86, s[100:101]
	s_lshl_b32 s4, s40, 1
	s_add_u32 s100, s100, s4
	s_addc_u32 s101, s101, 0
	global_load_dwordx2 v[46:47], v86, s[100:101]
	s_lshl_b32 s4, s40, 1
	s_add_u32 s100, s100, s4
	s_addc_u32 s101, s101, 0
	global_load_dwordx2 v[48:49], v86, s[100:101]
	s_mul_i32 s4, s40, 26
	s_add_u32 s100, s100, s4
	s_addc_u32 s101, s101, 0
	global_load_dwordx2 v[50:51], v86, s[100:101]
	s_lshl_b32 s4, s40, 1
	s_add_u32 s100, s100, s4
	s_addc_u32 s101, s101, 0
	global_load_dwordx2 v[52:53], v86, s[100:101]
	s_lshl_b32 s4, s40, 1
	s_add_u32 s100, s100, s4
	s_addc_u32 s101, s101, 0
	global_load_dwordx2 v[54:55], v86, s[100:101]
	s_lshl_b32 s4, s40, 1
	s_add_u32 s100, s100, s4
	s_addc_u32 s101, s101, 0
	global_load_dwordx2 v[56:57], v86, s[100:101]
	s_mul_i32 s4, s40, 26
	s_add_u32 s100, s100, s4
	s_addc_u32 s101, s101, 0
	global_load_dwordx2 v[58:59], v86, s[100:101]
	s_lshl_b32 s4, s40, 1
	s_add_u32 s100, s100, s4
	s_addc_u32 s101, s101, 0
	global_load_dwordx2 v[60:61], v86, s[100:101]
	s_lshl_b32 s4, s40, 1
	s_add_u32 s100, s100, s4
	s_addc_u32 s101, s101, 0
	global_load_dwordx2 v[62:63], v86, s[100:101]
	s_lshl_b32 s4, s40, 1
	s_add_u32 s100, s100, s4
	s_addc_u32 s101, s101, 0
	global_load_dwordx2 v[64:65], v86, s[100:101]
	s_mul_i32 s4, s40, 26
	s_add_u32 s100, s100, s4
	s_addc_u32 s101, s101, 0
	global_load_dwordx2 v[66:67], v86, s[100:101]
	s_lshl_b32 s4, s40, 1
	s_add_u32 s100, s100, s4
	s_addc_u32 s101, s101, 0
	global_load_dwordx2 v[68:69], v86, s[100:101]
	s_lshl_b32 s4, s40, 1
	s_add_u32 s100, s100, s4
	s_addc_u32 s101, s101, 0
	global_load_dwordx2 v[70:71], v86, s[100:101]
	s_lshl_b32 s4, s40, 1
	s_add_u32 s100, s100, s4
	s_addc_u32 s101, s101, 0
	global_load_dwordx2 v[72:73], v86, s[100:101]
	s_mul_i32 s4, s40, 26
	s_add_u32 s100, s100, s4
	s_addc_u32 s101, s101, 0
	global_load_dwordx2 v[74:75], v86, s[100:101]
	s_lshl_b32 s4, s40, 1
	s_add_u32 s100, s100, s4
	s_addc_u32 s101, s101, 0
	global_load_dwordx2 v[76:77], v86, s[100:101]
	s_lshl_b32 s4, s40, 1
	s_add_u32 s100, s100, s4
	s_addc_u32 s101, s101, 0
	global_load_dwordx2 v[78:79], v86, s[100:101]
	s_lshl_b32 s4, s40, 1
	s_add_u32 s100, s100, s4
	s_addc_u32 s101, s101, 0
	global_load_dwordx2 v[80:81], v86, s[100:101]
	s_mul_i32 s4, s40, 26
	s_add_u32 s100, s100, s4
	s_addc_u32 s101, s101, 0
	global_load_dwordx2 v[92:93], v86, s[100:101]
	s_lshl_b32 s4, s40, 1
	s_add_u32 s100, s100, s4
	s_addc_u32 s101, s101, 0
	global_load_dwordx2 v[94:95], v86, s[100:101]
	s_lshl_b32 s4, s40, 1
	s_add_u32 s100, s100, s4
	s_addc_u32 s101, s101, 0
	global_load_dwordx2 v[96:97], v86, s[100:101]
	s_lshl_b32 s4, s40, 1
	s_add_u32 s100, s100, s4
	s_addc_u32 s101, s101, 0
	global_load_dwordx2 v[98:99], v86, s[100:101]
	s_mul_i32 s4, s40, 26
	s_add_u32 s100, s100, s4
	s_addc_u32 s101, s101, 0
	global_load_dwordx2 v[100:101], v86, s[100:101]
	s_lshl_b32 s4, s40, 1
	s_add_u32 s100, s100, s4
	s_addc_u32 s101, s101, 0
	global_load_dwordx2 v[102:103], v86, s[100:101]
	s_lshl_b32 s4, s40, 1
	s_add_u32 s100, s100, s4
	s_addc_u32 s101, s101, 0
	global_load_dwordx2 v[104:105], v86, s[100:101]
	s_lshl_b32 s4, s40, 1
	s_add_u32 s100, s100, s4
	s_addc_u32 s101, s101, 0
	global_load_dwordx2 v[106:107], v86, s[100:101]
	s_mul_i32 s4, s40, 26
	s_add_u32 s100, s100, s4
	s_addc_u32 s101, s101, 0
	global_load_dwordx2 v[108:109], v86, s[100:101]
	s_lshl_b32 s4, s40, 1
	s_add_u32 s100, s100, s4
	s_addc_u32 s101, s101, 0
	global_load_dwordx2 v[110:111], v86, s[100:101]
	s_lshl_b32 s4, s40, 1
	s_add_u32 s100, s100, s4
	s_addc_u32 s101, s101, 0
	global_load_dwordx2 v[112:113], v86, s[100:101]
	s_lshl_b32 s4, s40, 1
	s_add_u32 s100, s100, s4
	s_addc_u32 s101, s101, 0
	global_load_dwordx2 v[114:115], v86, s[100:101]
	s_mul_i32 s4, s40, 26
	s_add_u32 s100, s100, s4
	s_addc_u32 s101, s101, 0
	global_load_dwordx2 v[116:117], v86, s[100:101]
	s_lshl_b32 s4, s40, 1
	s_add_u32 s100, s100, s4
	s_addc_u32 s101, s101, 0
	global_load_dwordx2 v[118:119], v86, s[100:101]
	s_lshl_b32 s4, s40, 1
	s_add_u32 s100, s100, s4
	s_addc_u32 s101, s101, 0
	global_load_dwordx2 v[120:121], v86, s[100:101]
	s_lshl_b32 s4, s40, 1
	s_add_u32 s100, s100, s4
	s_addc_u32 s101, s101, 0
	global_load_dwordx2 v[122:123], v86, s[100:101]
	s_mul_i32 s4, s40, 26
	s_add_u32 s100, s100, s4
	s_addc_u32 s101, s101, 0
	global_load_dwordx2 v[124:125], v86, s[100:101]
	s_lshl_b32 s4, s40, 1
	s_add_u32 s100, s100, s4
	s_addc_u32 s101, s101, 0
	global_load_dwordx2 v[126:127], v86, s[100:101]
	s_lshl_b32 s4, s40, 1
	s_add_u32 s100, s100, s4
	s_addc_u32 s101, s101, 0
	global_load_dwordx2 v[128:129], v86, s[100:101]
	s_lshl_b32 s4, s40, 1
	s_add_u32 s100, s100, s4
	s_addc_u32 s101, s101, 0
	global_load_dwordx2 v[130:131], v86, s[100:101]
	s_mul_i32 s4, s40, 26
	s_add_u32 s100, s100, s4
	s_addc_u32 s101, s101, 0
	global_load_dwordx2 v[132:133], v86, s[100:101]
	s_lshl_b32 s4, s40, 1
	s_add_u32 s100, s100, s4
	s_addc_u32 s101, s101, 0
	global_load_dwordx2 v[134:135], v86, s[100:101]
	s_lshl_b32 s4, s40, 1
	s_add_u32 s100, s100, s4
	s_addc_u32 s101, s101, 0
	global_load_dwordx2 v[136:137], v86, s[100:101]
	s_lshl_b32 s4, s40, 1
	s_add_u32 s100, s100, s4
	s_addc_u32 s101, s101, 0
	global_load_dwordx2 v[138:139], v86, s[100:101]
	s_mul_i32 s4, s40, 26
	s_add_u32 s100, s100, s4
	s_addc_u32 s101, s101, 0
	global_load_dwordx2 v[140:141], v86, s[100:101]
	s_lshl_b32 s4, s40, 1
	s_add_u32 s100, s100, s4
	s_addc_u32 s101, s101, 0
	global_load_dwordx2 v[142:143], v86, s[100:101]
	s_lshl_b32 s4, s40, 1
	s_add_u32 s100, s100, s4
	s_addc_u32 s101, s101, 0
	global_load_dwordx2 v[144:145], v86, s[100:101]
	s_lshl_b32 s4, s40, 1
	s_add_u32 s100, s100, s4
	s_addc_u32 s101, s101, 0
	global_load_dwordx2 v[146:147], v86, s[100:101]
	s_mul_i32 s4, s40, 26
	s_add_u32 s100, s100, s4
	s_addc_u32 s101, s101, 0
	global_load_dwordx2 v[148:149], v86, s[100:101]
	s_lshl_b32 s4, s40, 1
	s_add_u32 s100, s100, s4
	s_addc_u32 s101, s101, 0
	global_load_dwordx2 v[150:151], v86, s[100:101]
	s_lshl_b32 s4, s40, 1
	s_add_u32 s100, s100, s4
	s_addc_u32 s101, s101, 0
	global_load_dwordx2 v[152:153], v86, s[100:101]
	s_lshl_b32 s4, s40, 1
	s_add_u32 s100, s100, s4
	s_addc_u32 s101, s101, 0
	global_load_dwordx2 v[154:155], v86, s[100:101]
	s_mul_i32 s4, s40, 26
	s_add_u32 s100, s100, s4
	s_addc_u32 s101, s101, 0
	global_load_dwordx2 v[156:157], v86, s[100:101]
	s_lshl_b32 s4, s40, 1
	s_add_u32 s100, s100, s4
	s_addc_u32 s101, s101, 0
	global_load_dwordx2 v[158:159], v86, s[100:101]
	s_lshl_b32 s4, s40, 1
	s_add_u32 s100, s100, s4
	s_addc_u32 s101, s101, 0
	global_load_dwordx2 v[160:161], v86, s[100:101]
	s_lshl_b32 s4, s40, 1
	s_add_u32 s100, s100, s4
	s_addc_u32 s101, s101, 0
	global_load_dwordx2 v[162:163], v86, s[100:101]
	s_mul_i32 s4, s40, 26
	s_add_u32 s100, s100, s4
	s_addc_u32 s101, s101, 0
	s_waitcnt vmcnt(60)
	v_cndmask_b32_e64 v192, v27, v26, vcc
	v_cndmask_b32_e64 v193, v29, v28, vcc
	v_cndmask_b32_e64 v194, v31, v30, vcc
	v_cndmask_b32_e64 v195, v33, v32, vcc
	v_mov_b32_dpp v196, v192 quad_perm:[1,0,3,2] row_mask:0xf bank_mask:0xf
	v_mov_b32_dpp v197, v193 quad_perm:[1,0,3,2] row_mask:0xf bank_mask:0xf
	v_mov_b32_dpp v198, v194 quad_perm:[1,0,3,2] row_mask:0xf bank_mask:0xf
	v_mov_b32_dpp v199, v195 quad_perm:[1,0,3,2] row_mask:0xf bank_mask:0xf
	v_cndmask_b32_e64 v26, v26, v196, vcc
	v_cndmask_b32_e64 v27, v196, v27, vcc
	v_cndmask_b32_e64 v28, v28, v197, vcc
	v_cndmask_b32_e64 v29, v197, v29, vcc
	v_cndmask_b32_e64 v30, v30, v198, vcc
	v_cndmask_b32_e64 v31, v198, v31, vcc
	v_cndmask_b32_e64 v32, v32, v199, vcc
	v_cndmask_b32_e64 v33, v199, v33, vcc
	v_cvt_pk_bf16_f32 v14, v26, v27
	v_cvt_pk_bf16_f32 v15, v28, v29
	v_cvt_pk_bf16_f32 v16, v30, v31
	v_cvt_pk_bf16_f32 v17, v32, v33
	v_lshlrev_b32_e32 v84, 16, v14
	v_and_b32_e32 v85, 0xffff0000, v14
	v_sub_f32_e32 v26, v26, v84
	v_sub_f32_e32 v27, v27, v85
	v_cvt_pk_bf16_f32 v188, v26, v27
	v_lshlrev_b32_e32 v84, 16, v15
	v_and_b32_e32 v85, 0xffff0000, v15
	v_sub_f32_e32 v28, v28, v84
	v_sub_f32_e32 v29, v29, v85
	v_cvt_pk_bf16_f32 v189, v28, v29
	v_lshlrev_b32_e32 v84, 16, v16
	v_and_b32_e32 v85, 0xffff0000, v16
	v_sub_f32_e32 v30, v30, v84
	v_sub_f32_e32 v31, v31, v85
	v_cvt_pk_bf16_f32 v190, v30, v31
	v_lshlrev_b32_e32 v84, 16, v17
	v_and_b32_e32 v85, 0xffff0000, v17
	v_sub_f32_e32 v32, v32, v84
	v_sub_f32_e32 v33, v33, v85
	v_cvt_pk_bf16_f32 v191, v32, v33
	global_load_dwordx2 v[26:27], v86, s[100:101]
	s_lshl_b32 s4, s40, 1
	s_add_u32 s100, s100, s4
	s_addc_u32 s101, s101, 0
	global_load_dwordx2 v[28:29], v86, s[100:101]
	s_lshl_b32 s4, s40, 1
	s_add_u32 s100, s100, s4
	s_addc_u32 s101, s101, 0
	global_load_dwordx2 v[30:31], v86, s[100:101]
	s_lshl_b32 s4, s40, 1
	s_add_u32 s100, s100, s4
	s_addc_u32 s101, s101, 0
	global_load_dwordx2 v[32:33], v86, s[100:101]
	s_mul_i32 s4, s40, 26
	s_add_u32 s100, s100, s4
	s_addc_u32 s101, s101, 0
	s_waitcnt lgkmcnt(0)
	v_mfma_f32_16x16x32_bf16 v[10:13], v[164:167], v[14:17], v[10:13]
	v_mfma_f32_16x16x32_bf16 v[6:9], v[172:175], v[14:17], v[6:9]
	v_mfma_f32_16x16x32_bf16 v[2:5], v[180:183], v[14:17], v[2:5]
	v_mfma_f32_16x16x32_bf16 v[10:13], v[164:167], v[188:191], v[10:13]
	ds_read_b128 v[164:167], v87 offset:64
	v_mfma_f32_16x16x32_bf16 v[6:9], v[172:175], v[188:191], v[6:9]
	ds_read_b128 v[172:175], v87 offset:33088
	v_mfma_f32_16x16x32_bf16 v[2:5], v[180:183], v[188:191], v[2:5]
	ds_read_b128 v[180:183], v89 offset:64
	v_mfma_f32_16x16x32_bf16 v[10:13], v[168:171], v[14:17], v[10:13]
	ds_read_b128 v[168:171], v88 offset:64
	v_mfma_f32_16x16x32_bf16 v[6:9], v[176:179], v[14:17], v[6:9]
	ds_read_b128 v[176:179], v88 offset:33088
	v_mfma_f32_16x16x32_bf16 v[2:5], v[184:187], v[14:17], v[2:5]
	ds_read_b128 v[184:187], v200 offset:64
	s_waitcnt vmcnt(60)
	v_cndmask_b32_e64 v192, v35, v34, vcc
	v_cndmask_b32_e64 v193, v37, v36, vcc
	v_cndmask_b32_e64 v194, v39, v38, vcc
	v_cndmask_b32_e64 v195, v41, v40, vcc
	v_mov_b32_dpp v196, v192 quad_perm:[1,0,3,2] row_mask:0xf bank_mask:0xf
	v_mov_b32_dpp v197, v193 quad_perm:[1,0,3,2] row_mask:0xf bank_mask:0xf
	v_mov_b32_dpp v198, v194 quad_perm:[1,0,3,2] row_mask:0xf bank_mask:0xf
	v_mov_b32_dpp v199, v195 quad_perm:[1,0,3,2] row_mask:0xf bank_mask:0xf
	v_cndmask_b32_e64 v34, v34, v196, vcc
	v_cndmask_b32_e64 v35, v196, v35, vcc
	v_cndmask_b32_e64 v36, v36, v197, vcc
	v_cndmask_b32_e64 v37, v197, v37, vcc
	v_cndmask_b32_e64 v38, v38, v198, vcc
	v_cndmask_b32_e64 v39, v198, v39, vcc
	v_cndmask_b32_e64 v40, v40, v199, vcc
	v_cndmask_b32_e64 v41, v199, v41, vcc
	v_cvt_pk_bf16_f32 v14, v34, v35
	v_cvt_pk_bf16_f32 v15, v36, v37
	v_cvt_pk_bf16_f32 v16, v38, v39
	v_cvt_pk_bf16_f32 v17, v40, v41
	v_lshlrev_b32_e32 v84, 16, v14
	v_and_b32_e32 v85, 0xffff0000, v14
	v_sub_f32_e32 v34, v34, v84
	v_sub_f32_e32 v35, v35, v85
	v_cvt_pk_bf16_f32 v188, v34, v35
	v_lshlrev_b32_e32 v84, 16, v15
	v_and_b32_e32 v85, 0xffff0000, v15
	v_sub_f32_e32 v36, v36, v84
	v_sub_f32_e32 v37, v37, v85
	v_cvt_pk_bf16_f32 v189, v36, v37
	v_lshlrev_b32_e32 v84, 16, v16
	v_and_b32_e32 v85, 0xffff0000, v16
	v_sub_f32_e32 v38, v38, v84
	v_sub_f32_e32 v39, v39, v85
	v_cvt_pk_bf16_f32 v190, v38, v39
	v_lshlrev_b32_e32 v84, 16, v17
	v_and_b32_e32 v85, 0xffff0000, v17
	v_sub_f32_e32 v40, v40, v84
	v_sub_f32_e32 v41, v41, v85
	v_cvt_pk_bf16_f32 v191, v40, v41
	global_load_dwordx2 v[34:35], v86, s[100:101]
	s_lshl_b32 s4, s40, 1
	s_add_u32 s100, s100, s4
	s_addc_u32 s101, s101, 0
	global_load_dwordx2 v[36:37], v86, s[100:101]
	s_lshl_b32 s4, s40, 1
	s_add_u32 s100, s100, s4
	s_addc_u32 s101, s101, 0
	global_load_dwordx2 v[38:39], v86, s[100:101]
	s_lshl_b32 s4, s40, 1
	s_add_u32 s100, s100, s4
	s_addc_u32 s101, s101, 0
	global_load_dwordx2 v[40:41], v86, s[100:101]
	s_mul_i32 s4, s40, 26
	s_add_u32 s100, s100, s4
	s_addc_u32 s101, s101, 0
	s_waitcnt lgkmcnt(0)
	v_mfma_f32_16x16x32_bf16 v[10:13], v[164:167], v[14:17], v[10:13]
	v_mfma_f32_16x16x32_bf16 v[6:9], v[172:175], v[14:17], v[6:9]
	v_mfma_f32_16x16x32_bf16 v[2:5], v[180:183], v[14:17], v[2:5]
	v_mfma_f32_16x16x32_bf16 v[10:13], v[164:167], v[188:191], v[10:13]
	ds_read_b128 v[164:167], v87 offset:128
	v_mfma_f32_16x16x32_bf16 v[6:9], v[172:175], v[188:191], v[6:9]
	ds_read_b128 v[172:175], v87 offset:33152
	v_mfma_f32_16x16x32_bf16 v[2:5], v[180:183], v[188:191], v[2:5]
	ds_read_b128 v[180:183], v89 offset:128
	v_mfma_f32_16x16x32_bf16 v[10:13], v[168:171], v[14:17], v[10:13]
	ds_read_b128 v[168:171], v88 offset:128
	v_mfma_f32_16x16x32_bf16 v[6:9], v[176:179], v[14:17], v[6:9]
	ds_read_b128 v[176:179], v88 offset:33152
	v_mfma_f32_16x16x32_bf16 v[2:5], v[184:187], v[14:17], v[2:5]
	ds_read_b128 v[184:187], v200 offset:128
	s_waitcnt vmcnt(60)
	v_cndmask_b32_e64 v192, v43, v42, vcc
	v_cndmask_b32_e64 v193, v45, v44, vcc
	v_cndmask_b32_e64 v194, v47, v46, vcc
	v_cndmask_b32_e64 v195, v49, v48, vcc
	v_mov_b32_dpp v196, v192 quad_perm:[1,0,3,2] row_mask:0xf bank_mask:0xf
	v_mov_b32_dpp v197, v193 quad_perm:[1,0,3,2] row_mask:0xf bank_mask:0xf
	v_mov_b32_dpp v198, v194 quad_perm:[1,0,3,2] row_mask:0xf bank_mask:0xf
	v_mov_b32_dpp v199, v195 quad_perm:[1,0,3,2] row_mask:0xf bank_mask:0xf
	v_cndmask_b32_e64 v42, v42, v196, vcc
	v_cndmask_b32_e64 v43, v196, v43, vcc
	v_cndmask_b32_e64 v44, v44, v197, vcc
	v_cndmask_b32_e64 v45, v197, v45, vcc
	v_cndmask_b32_e64 v46, v46, v198, vcc
	v_cndmask_b32_e64 v47, v198, v47, vcc
	v_cndmask_b32_e64 v48, v48, v199, vcc
	v_cndmask_b32_e64 v49, v199, v49, vcc
	v_cvt_pk_bf16_f32 v14, v42, v43
	v_cvt_pk_bf16_f32 v15, v44, v45
	v_cvt_pk_bf16_f32 v16, v46, v47
	v_cvt_pk_bf16_f32 v17, v48, v49
	v_lshlrev_b32_e32 v84, 16, v14
	v_and_b32_e32 v85, 0xffff0000, v14
	v_sub_f32_e32 v42, v42, v84
	v_sub_f32_e32 v43, v43, v85
	v_cvt_pk_bf16_f32 v188, v42, v43
	v_lshlrev_b32_e32 v84, 16, v15
	v_and_b32_e32 v85, 0xffff0000, v15
	v_sub_f32_e32 v44, v44, v84
	v_sub_f32_e32 v45, v45, v85
	v_cvt_pk_bf16_f32 v189, v44, v45
	v_lshlrev_b32_e32 v84, 16, v16
	v_and_b32_e32 v85, 0xffff0000, v16
	v_sub_f32_e32 v46, v46, v84
	v_sub_f32_e32 v47, v47, v85
	v_cvt_pk_bf16_f32 v190, v46, v47
	v_lshlrev_b32_e32 v84, 16, v17
	v_and_b32_e32 v85, 0xffff0000, v17
	v_sub_f32_e32 v48, v48, v84
	v_sub_f32_e32 v49, v49, v85
	v_cvt_pk_bf16_f32 v191, v48, v49
	global_load_dwordx2 v[42:43], v86, s[100:101]
	s_lshl_b32 s4, s40, 1
	s_add_u32 s100, s100, s4
	s_addc_u32 s101, s101, 0
	global_load_dwordx2 v[44:45], v86, s[100:101]
	s_lshl_b32 s4, s40, 1
	s_add_u32 s100, s100, s4
	s_addc_u32 s101, s101, 0
	global_load_dwordx2 v[46:47], v86, s[100:101]
	s_lshl_b32 s4, s40, 1
	s_add_u32 s100, s100, s4
	s_addc_u32 s101, s101, 0
	global_load_dwordx2 v[48:49], v86, s[100:101]
	s_mul_i32 s4, s40, 26
	s_add_u32 s100, s100, s4
	s_addc_u32 s101, s101, 0
	s_waitcnt lgkmcnt(0)
	v_mfma_f32_16x16x32_bf16 v[10:13], v[164:167], v[14:17], v[10:13]
	v_mfma_f32_16x16x32_bf16 v[6:9], v[172:175], v[14:17], v[6:9]
	v_mfma_f32_16x16x32_bf16 v[2:5], v[180:183], v[14:17], v[2:5]
	v_mfma_f32_16x16x32_bf16 v[10:13], v[164:167], v[188:191], v[10:13]
	ds_read_b128 v[164:167], v87 offset:192
	v_mfma_f32_16x16x32_bf16 v[6:9], v[172:175], v[188:191], v[6:9]
	ds_read_b128 v[172:175], v87 offset:33216
	v_mfma_f32_16x16x32_bf16 v[2:5], v[180:183], v[188:191], v[2:5]
	ds_read_b128 v[180:183], v89 offset:192
	v_mfma_f32_16x16x32_bf16 v[10:13], v[168:171], v[14:17], v[10:13]
	ds_read_b128 v[168:171], v88 offset:192
	v_mfma_f32_16x16x32_bf16 v[6:9], v[176:179], v[14:17], v[6:9]
	ds_read_b128 v[176:179], v88 offset:33216
	v_mfma_f32_16x16x32_bf16 v[2:5], v[184:187], v[14:17], v[2:5]
	ds_read_b128 v[184:187], v200 offset:192
	s_waitcnt vmcnt(60)
	v_cndmask_b32_e64 v192, v51, v50, vcc
	v_cndmask_b32_e64 v193, v53, v52, vcc
	v_cndmask_b32_e64 v194, v55, v54, vcc
	v_cndmask_b32_e64 v195, v57, v56, vcc
	v_mov_b32_dpp v196, v192 quad_perm:[1,0,3,2] row_mask:0xf bank_mask:0xf
	v_mov_b32_dpp v197, v193 quad_perm:[1,0,3,2] row_mask:0xf bank_mask:0xf
	v_mov_b32_dpp v198, v194 quad_perm:[1,0,3,2] row_mask:0xf bank_mask:0xf
	v_mov_b32_dpp v199, v195 quad_perm:[1,0,3,2] row_mask:0xf bank_mask:0xf
	v_cndmask_b32_e64 v50, v50, v196, vcc
	v_cndmask_b32_e64 v51, v196, v51, vcc
	v_cndmask_b32_e64 v52, v52, v197, vcc
	v_cndmask_b32_e64 v53, v197, v53, vcc
	v_cndmask_b32_e64 v54, v54, v198, vcc
	v_cndmask_b32_e64 v55, v198, v55, vcc
	v_cndmask_b32_e64 v56, v56, v199, vcc
	v_cndmask_b32_e64 v57, v199, v57, vcc
	v_cvt_pk_bf16_f32 v14, v50, v51
	v_cvt_pk_bf16_f32 v15, v52, v53
	v_cvt_pk_bf16_f32 v16, v54, v55
	v_cvt_pk_bf16_f32 v17, v56, v57
	v_lshlrev_b32_e32 v84, 16, v14
	v_and_b32_e32 v85, 0xffff0000, v14
	v_sub_f32_e32 v50, v50, v84
	v_sub_f32_e32 v51, v51, v85
	v_cvt_pk_bf16_f32 v188, v50, v51
	v_lshlrev_b32_e32 v84, 16, v15
	v_and_b32_e32 v85, 0xffff0000, v15
	v_sub_f32_e32 v52, v52, v84
	v_sub_f32_e32 v53, v53, v85
	v_cvt_pk_bf16_f32 v189, v52, v53
	v_lshlrev_b32_e32 v84, 16, v16
	v_and_b32_e32 v85, 0xffff0000, v16
	v_sub_f32_e32 v54, v54, v84
	v_sub_f32_e32 v55, v55, v85
	v_cvt_pk_bf16_f32 v190, v54, v55
	v_lshlrev_b32_e32 v84, 16, v17
	v_and_b32_e32 v85, 0xffff0000, v17
	v_sub_f32_e32 v56, v56, v84
	v_sub_f32_e32 v57, v57, v85
	v_cvt_pk_bf16_f32 v191, v56, v57
	global_load_dwordx2 v[50:51], v86, s[100:101]
	s_lshl_b32 s4, s40, 1
	s_add_u32 s100, s100, s4
	s_addc_u32 s101, s101, 0
	global_load_dwordx2 v[52:53], v86, s[100:101]
	s_lshl_b32 s4, s40, 1
	s_add_u32 s100, s100, s4
	s_addc_u32 s101, s101, 0
	global_load_dwordx2 v[54:55], v86, s[100:101]
	s_lshl_b32 s4, s40, 1
	s_add_u32 s100, s100, s4
	s_addc_u32 s101, s101, 0
	global_load_dwordx2 v[56:57], v86, s[100:101]
	s_mul_i32 s4, s40, 26
	s_add_u32 s100, s100, s4
	s_addc_u32 s101, s101, 0
	s_waitcnt lgkmcnt(0)
	v_mfma_f32_16x16x32_bf16 v[10:13], v[164:167], v[14:17], v[10:13]
	v_mfma_f32_16x16x32_bf16 v[6:9], v[172:175], v[14:17], v[6:9]
	v_mfma_f32_16x16x32_bf16 v[2:5], v[180:183], v[14:17], v[2:5]
	v_mfma_f32_16x16x32_bf16 v[10:13], v[164:167], v[188:191], v[10:13]
	ds_read_b128 v[164:167], v87 offset:256
	v_mfma_f32_16x16x32_bf16 v[6:9], v[172:175], v[188:191], v[6:9]
	ds_read_b128 v[172:175], v87 offset:33280
	v_mfma_f32_16x16x32_bf16 v[2:5], v[180:183], v[188:191], v[2:5]
	ds_read_b128 v[180:183], v89 offset:256
	v_mfma_f32_16x16x32_bf16 v[10:13], v[168:171], v[14:17], v[10:13]
	ds_read_b128 v[168:171], v88 offset:256
	v_mfma_f32_16x16x32_bf16 v[6:9], v[176:179], v[14:17], v[6:9]
	ds_read_b128 v[176:179], v88 offset:33280
	v_mfma_f32_16x16x32_bf16 v[2:5], v[184:187], v[14:17], v[2:5]
	ds_read_b128 v[184:187], v200 offset:256
	s_waitcnt vmcnt(60)
	v_cndmask_b32_e64 v192, v59, v58, vcc
	v_cndmask_b32_e64 v193, v61, v60, vcc
	v_cndmask_b32_e64 v194, v63, v62, vcc
	v_cndmask_b32_e64 v195, v65, v64, vcc
	v_mov_b32_dpp v196, v192 quad_perm:[1,0,3,2] row_mask:0xf bank_mask:0xf
	v_mov_b32_dpp v197, v193 quad_perm:[1,0,3,2] row_mask:0xf bank_mask:0xf
	v_mov_b32_dpp v198, v194 quad_perm:[1,0,3,2] row_mask:0xf bank_mask:0xf
	v_mov_b32_dpp v199, v195 quad_perm:[1,0,3,2] row_mask:0xf bank_mask:0xf
	v_cndmask_b32_e64 v58, v58, v196, vcc
	v_cndmask_b32_e64 v59, v196, v59, vcc
	v_cndmask_b32_e64 v60, v60, v197, vcc
	v_cndmask_b32_e64 v61, v197, v61, vcc
	v_cndmask_b32_e64 v62, v62, v198, vcc
	v_cndmask_b32_e64 v63, v198, v63, vcc
	v_cndmask_b32_e64 v64, v64, v199, vcc
	v_cndmask_b32_e64 v65, v199, v65, vcc
	v_cvt_pk_bf16_f32 v14, v58, v59
	v_cvt_pk_bf16_f32 v15, v60, v61
	v_cvt_pk_bf16_f32 v16, v62, v63
	v_cvt_pk_bf16_f32 v17, v64, v65
	v_lshlrev_b32_e32 v84, 16, v14
	v_and_b32_e32 v85, 0xffff0000, v14
	v_sub_f32_e32 v58, v58, v84
	v_sub_f32_e32 v59, v59, v85
	v_cvt_pk_bf16_f32 v188, v58, v59
	v_lshlrev_b32_e32 v84, 16, v15
	v_and_b32_e32 v85, 0xffff0000, v15
	v_sub_f32_e32 v60, v60, v84
	v_sub_f32_e32 v61, v61, v85
	v_cvt_pk_bf16_f32 v189, v60, v61
	v_lshlrev_b32_e32 v84, 16, v16
	v_and_b32_e32 v85, 0xffff0000, v16
	v_sub_f32_e32 v62, v62, v84
	v_sub_f32_e32 v63, v63, v85
	v_cvt_pk_bf16_f32 v190, v62, v63
	v_lshlrev_b32_e32 v84, 16, v17
	v_and_b32_e32 v85, 0xffff0000, v17
	v_sub_f32_e32 v64, v64, v84
	v_sub_f32_e32 v65, v65, v85
	v_cvt_pk_bf16_f32 v191, v64, v65
	global_load_dwordx2 v[58:59], v86, s[100:101]
	s_lshl_b32 s4, s40, 1
	s_add_u32 s100, s100, s4
	s_addc_u32 s101, s101, 0
	global_load_dwordx2 v[60:61], v86, s[100:101]
	s_lshl_b32 s4, s40, 1
	s_add_u32 s100, s100, s4
	s_addc_u32 s101, s101, 0
	global_load_dwordx2 v[62:63], v86, s[100:101]
	s_lshl_b32 s4, s40, 1
	s_add_u32 s100, s100, s4
	s_addc_u32 s101, s101, 0
	global_load_dwordx2 v[64:65], v86, s[100:101]
	s_mul_i32 s4, s40, 26
	s_add_u32 s100, s100, s4
	s_addc_u32 s101, s101, 0
	s_waitcnt lgkmcnt(0)
	v_mfma_f32_16x16x32_bf16 v[10:13], v[164:167], v[14:17], v[10:13]
	v_mfma_f32_16x16x32_bf16 v[6:9], v[172:175], v[14:17], v[6:9]
	v_mfma_f32_16x16x32_bf16 v[2:5], v[180:183], v[14:17], v[2:5]
	v_mfma_f32_16x16x32_bf16 v[10:13], v[164:167], v[188:191], v[10:13]
	ds_read_b128 v[164:167], v87 offset:320
	v_mfma_f32_16x16x32_bf16 v[6:9], v[172:175], v[188:191], v[6:9]
	ds_read_b128 v[172:175], v87 offset:33344
	v_mfma_f32_16x16x32_bf16 v[2:5], v[180:183], v[188:191], v[2:5]
	ds_read_b128 v[180:183], v89 offset:320
	v_mfma_f32_16x16x32_bf16 v[10:13], v[168:171], v[14:17], v[10:13]
	ds_read_b128 v[168:171], v88 offset:320
	v_mfma_f32_16x16x32_bf16 v[6:9], v[176:179], v[14:17], v[6:9]
	ds_read_b128 v[176:179], v88 offset:33344
	v_mfma_f32_16x16x32_bf16 v[2:5], v[184:187], v[14:17], v[2:5]
	ds_read_b128 v[184:187], v200 offset:320
	s_waitcnt vmcnt(60)
	v_cndmask_b32_e64 v192, v67, v66, vcc
	v_cndmask_b32_e64 v193, v69, v68, vcc
	v_cndmask_b32_e64 v194, v71, v70, vcc
	v_cndmask_b32_e64 v195, v73, v72, vcc
	v_mov_b32_dpp v196, v192 quad_perm:[1,0,3,2] row_mask:0xf bank_mask:0xf
	v_mov_b32_dpp v197, v193 quad_perm:[1,0,3,2] row_mask:0xf bank_mask:0xf
	v_mov_b32_dpp v198, v194 quad_perm:[1,0,3,2] row_mask:0xf bank_mask:0xf
	v_mov_b32_dpp v199, v195 quad_perm:[1,0,3,2] row_mask:0xf bank_mask:0xf
	v_cndmask_b32_e64 v66, v66, v196, vcc
	v_cndmask_b32_e64 v67, v196, v67, vcc
	v_cndmask_b32_e64 v68, v68, v197, vcc
	v_cndmask_b32_e64 v69, v197, v69, vcc
	v_cndmask_b32_e64 v70, v70, v198, vcc
	v_cndmask_b32_e64 v71, v198, v71, vcc
	v_cndmask_b32_e64 v72, v72, v199, vcc
	v_cndmask_b32_e64 v73, v199, v73, vcc
	v_cvt_pk_bf16_f32 v14, v66, v67
	v_cvt_pk_bf16_f32 v15, v68, v69
	v_cvt_pk_bf16_f32 v16, v70, v71
	v_cvt_pk_bf16_f32 v17, v72, v73
	v_lshlrev_b32_e32 v84, 16, v14
	v_and_b32_e32 v85, 0xffff0000, v14
	v_sub_f32_e32 v66, v66, v84
	v_sub_f32_e32 v67, v67, v85
	v_cvt_pk_bf16_f32 v188, v66, v67
	v_lshlrev_b32_e32 v84, 16, v15
	v_and_b32_e32 v85, 0xffff0000, v15
	v_sub_f32_e32 v68, v68, v84
	v_sub_f32_e32 v69, v69, v85
	v_cvt_pk_bf16_f32 v189, v68, v69
	v_lshlrev_b32_e32 v84, 16, v16
	v_and_b32_e32 v85, 0xffff0000, v16
	v_sub_f32_e32 v70, v70, v84
	v_sub_f32_e32 v71, v71, v85
	v_cvt_pk_bf16_f32 v190, v70, v71
	v_lshlrev_b32_e32 v84, 16, v17
	v_and_b32_e32 v85, 0xffff0000, v17
	v_sub_f32_e32 v72, v72, v84
	v_sub_f32_e32 v73, v73, v85
	v_cvt_pk_bf16_f32 v191, v72, v73
	global_load_dwordx2 v[66:67], v86, s[100:101]
	s_lshl_b32 s4, s40, 1
	s_add_u32 s100, s100, s4
	s_addc_u32 s101, s101, 0
	global_load_dwordx2 v[68:69], v86, s[100:101]
	s_lshl_b32 s4, s40, 1
	s_add_u32 s100, s100, s4
	s_addc_u32 s101, s101, 0
	global_load_dwordx2 v[70:71], v86, s[100:101]
	s_lshl_b32 s4, s40, 1
	s_add_u32 s100, s100, s4
	s_addc_u32 s101, s101, 0
	global_load_dwordx2 v[72:73], v86, s[100:101]
	s_mul_i32 s4, s40, 26
	s_add_u32 s100, s100, s4
	s_addc_u32 s101, s101, 0
	s_waitcnt lgkmcnt(0)
	v_mfma_f32_16x16x32_bf16 v[10:13], v[164:167], v[14:17], v[10:13]
	v_mfma_f32_16x16x32_bf16 v[6:9], v[172:175], v[14:17], v[6:9]
	v_mfma_f32_16x16x32_bf16 v[2:5], v[180:183], v[14:17], v[2:5]
	v_mfma_f32_16x16x32_bf16 v[10:13], v[164:167], v[188:191], v[10:13]
	ds_read_b128 v[164:167], v87 offset:384
	v_mfma_f32_16x16x32_bf16 v[6:9], v[172:175], v[188:191], v[6:9]
	ds_read_b128 v[172:175], v87 offset:33408
	v_mfma_f32_16x16x32_bf16 v[2:5], v[180:183], v[188:191], v[2:5]
	ds_read_b128 v[180:183], v89 offset:384
	v_mfma_f32_16x16x32_bf16 v[10:13], v[168:171], v[14:17], v[10:13]
	ds_read_b128 v[168:171], v88 offset:384
	v_mfma_f32_16x16x32_bf16 v[6:9], v[176:179], v[14:17], v[6:9]
	ds_read_b128 v[176:179], v88 offset:33408
	v_mfma_f32_16x16x32_bf16 v[2:5], v[184:187], v[14:17], v[2:5]
	ds_read_b128 v[184:187], v200 offset:384
	s_waitcnt vmcnt(60)
	v_cndmask_b32_e64 v192, v75, v74, vcc
	v_cndmask_b32_e64 v193, v77, v76, vcc
	v_cndmask_b32_e64 v194, v79, v78, vcc
	v_cndmask_b32_e64 v195, v81, v80, vcc
	v_mov_b32_dpp v196, v192 quad_perm:[1,0,3,2] row_mask:0xf bank_mask:0xf
	v_mov_b32_dpp v197, v193 quad_perm:[1,0,3,2] row_mask:0xf bank_mask:0xf
	v_mov_b32_dpp v198, v194 quad_perm:[1,0,3,2] row_mask:0xf bank_mask:0xf
	v_mov_b32_dpp v199, v195 quad_perm:[1,0,3,2] row_mask:0xf bank_mask:0xf
	v_cndmask_b32_e64 v74, v74, v196, vcc
	v_cndmask_b32_e64 v75, v196, v75, vcc
	v_cndmask_b32_e64 v76, v76, v197, vcc
	v_cndmask_b32_e64 v77, v197, v77, vcc
	v_cndmask_b32_e64 v78, v78, v198, vcc
	v_cndmask_b32_e64 v79, v198, v79, vcc
	v_cndmask_b32_e64 v80, v80, v199, vcc
	v_cndmask_b32_e64 v81, v199, v81, vcc
	v_cvt_pk_bf16_f32 v14, v74, v75
	v_cvt_pk_bf16_f32 v15, v76, v77
	v_cvt_pk_bf16_f32 v16, v78, v79
	v_cvt_pk_bf16_f32 v17, v80, v81
	v_lshlrev_b32_e32 v84, 16, v14
	v_and_b32_e32 v85, 0xffff0000, v14
	v_sub_f32_e32 v74, v74, v84
	v_sub_f32_e32 v75, v75, v85
	v_cvt_pk_bf16_f32 v188, v74, v75
	v_lshlrev_b32_e32 v84, 16, v15
	v_and_b32_e32 v85, 0xffff0000, v15
	v_sub_f32_e32 v76, v76, v84
	v_sub_f32_e32 v77, v77, v85
	v_cvt_pk_bf16_f32 v189, v76, v77
	v_lshlrev_b32_e32 v84, 16, v16
	v_and_b32_e32 v85, 0xffff0000, v16
	v_sub_f32_e32 v78, v78, v84
	v_sub_f32_e32 v79, v79, v85
	v_cvt_pk_bf16_f32 v190, v78, v79
	v_lshlrev_b32_e32 v84, 16, v17
	v_and_b32_e32 v85, 0xffff0000, v17
	v_sub_f32_e32 v80, v80, v84
	v_sub_f32_e32 v81, v81, v85
	v_cvt_pk_bf16_f32 v191, v80, v81
	global_load_dwordx2 v[74:75], v86, s[100:101]
	s_lshl_b32 s4, s40, 1
	s_add_u32 s100, s100, s4
	s_addc_u32 s101, s101, 0
	global_load_dwordx2 v[76:77], v86, s[100:101]
	s_lshl_b32 s4, s40, 1
	s_add_u32 s100, s100, s4
	s_addc_u32 s101, s101, 0
	global_load_dwordx2 v[78:79], v86, s[100:101]
	s_lshl_b32 s4, s40, 1
	s_add_u32 s100, s100, s4
	s_addc_u32 s101, s101, 0
	global_load_dwordx2 v[80:81], v86, s[100:101]
	s_mul_i32 s4, s40, 26
	s_add_u32 s100, s100, s4
	s_addc_u32 s101, s101, 0
	s_waitcnt lgkmcnt(0)
	v_mfma_f32_16x16x32_bf16 v[10:13], v[164:167], v[14:17], v[10:13]
	v_mfma_f32_16x16x32_bf16 v[6:9], v[172:175], v[14:17], v[6:9]
	v_mfma_f32_16x16x32_bf16 v[2:5], v[180:183], v[14:17], v[2:5]
	v_mfma_f32_16x16x32_bf16 v[10:13], v[164:167], v[188:191], v[10:13]
	ds_read_b128 v[164:167], v87 offset:448
	v_mfma_f32_16x16x32_bf16 v[6:9], v[172:175], v[188:191], v[6:9]
	ds_read_b128 v[172:175], v87 offset:33472
	v_mfma_f32_16x16x32_bf16 v[2:5], v[180:183], v[188:191], v[2:5]
	ds_read_b128 v[180:183], v89 offset:448
	v_mfma_f32_16x16x32_bf16 v[10:13], v[168:171], v[14:17], v[10:13]
	ds_read_b128 v[168:171], v88 offset:448
	v_mfma_f32_16x16x32_bf16 v[6:9], v[176:179], v[14:17], v[6:9]
	ds_read_b128 v[176:179], v88 offset:33472
	v_mfma_f32_16x16x32_bf16 v[2:5], v[184:187], v[14:17], v[2:5]
	ds_read_b128 v[184:187], v200 offset:448
	s_waitcnt vmcnt(60)
	v_cndmask_b32_e64 v192, v93, v92, vcc
	v_cndmask_b32_e64 v193, v95, v94, vcc
	v_cndmask_b32_e64 v194, v97, v96, vcc
	v_cndmask_b32_e64 v195, v99, v98, vcc
	v_mov_b32_dpp v196, v192 quad_perm:[1,0,3,2] row_mask:0xf bank_mask:0xf
	v_mov_b32_dpp v197, v193 quad_perm:[1,0,3,2] row_mask:0xf bank_mask:0xf
	v_mov_b32_dpp v198, v194 quad_perm:[1,0,3,2] row_mask:0xf bank_mask:0xf
	v_mov_b32_dpp v199, v195 quad_perm:[1,0,3,2] row_mask:0xf bank_mask:0xf
	v_cndmask_b32_e64 v92, v92, v196, vcc
	v_cndmask_b32_e64 v93, v196, v93, vcc
	v_cndmask_b32_e64 v94, v94, v197, vcc
	v_cndmask_b32_e64 v95, v197, v95, vcc
	v_cndmask_b32_e64 v96, v96, v198, vcc
	v_cndmask_b32_e64 v97, v198, v97, vcc
	v_cndmask_b32_e64 v98, v98, v199, vcc
	v_cndmask_b32_e64 v99, v199, v99, vcc
	v_cvt_pk_bf16_f32 v14, v92, v93
	v_cvt_pk_bf16_f32 v15, v94, v95
	v_cvt_pk_bf16_f32 v16, v96, v97
	v_cvt_pk_bf16_f32 v17, v98, v99
	v_lshlrev_b32_e32 v84, 16, v14
	v_and_b32_e32 v85, 0xffff0000, v14
	v_sub_f32_e32 v92, v92, v84
	v_sub_f32_e32 v93, v93, v85
	v_cvt_pk_bf16_f32 v188, v92, v93
	v_lshlrev_b32_e32 v84, 16, v15
	v_and_b32_e32 v85, 0xffff0000, v15
	v_sub_f32_e32 v94, v94, v84
	v_sub_f32_e32 v95, v95, v85
	v_cvt_pk_bf16_f32 v189, v94, v95
	v_lshlrev_b32_e32 v84, 16, v16
	v_and_b32_e32 v85, 0xffff0000, v16
	v_sub_f32_e32 v96, v96, v84
	v_sub_f32_e32 v97, v97, v85
	v_cvt_pk_bf16_f32 v190, v96, v97
	v_lshlrev_b32_e32 v84, 16, v17
	v_and_b32_e32 v85, 0xffff0000, v17
	v_sub_f32_e32 v98, v98, v84
	v_sub_f32_e32 v99, v99, v85
	v_cvt_pk_bf16_f32 v191, v98, v99
	global_load_dwordx2 v[92:93], v86, s[100:101]
	s_lshl_b32 s4, s40, 1
	s_add_u32 s100, s100, s4
	s_addc_u32 s101, s101, 0
	global_load_dwordx2 v[94:95], v86, s[100:101]
	s_lshl_b32 s4, s40, 1
	s_add_u32 s100, s100, s4
	s_addc_u32 s101, s101, 0
	global_load_dwordx2 v[96:97], v86, s[100:101]
	s_lshl_b32 s4, s40, 1
	s_add_u32 s100, s100, s4
	s_addc_u32 s101, s101, 0
	global_load_dwordx2 v[98:99], v86, s[100:101]
	s_mul_i32 s4, s40, 26
	s_add_u32 s100, s100, s4
	s_addc_u32 s101, s101, 0
	s_waitcnt lgkmcnt(0)
	v_mfma_f32_16x16x32_bf16 v[10:13], v[164:167], v[14:17], v[10:13]
	v_mfma_f32_16x16x32_bf16 v[6:9], v[172:175], v[14:17], v[6:9]
	v_mfma_f32_16x16x32_bf16 v[2:5], v[180:183], v[14:17], v[2:5]
	v_mfma_f32_16x16x32_bf16 v[10:13], v[164:167], v[188:191], v[10:13]
	ds_read_b128 v[164:167], v87 offset:512
	v_mfma_f32_16x16x32_bf16 v[6:9], v[172:175], v[188:191], v[6:9]
	ds_read_b128 v[172:175], v87 offset:33536
	v_mfma_f32_16x16x32_bf16 v[2:5], v[180:183], v[188:191], v[2:5]
	ds_read_b128 v[180:183], v89 offset:512
	v_mfma_f32_16x16x32_bf16 v[10:13], v[168:171], v[14:17], v[10:13]
	ds_read_b128 v[168:171], v88 offset:512
	v_mfma_f32_16x16x32_bf16 v[6:9], v[176:179], v[14:17], v[6:9]
	ds_read_b128 v[176:179], v88 offset:33536
	v_mfma_f32_16x16x32_bf16 v[2:5], v[184:187], v[14:17], v[2:5]
	ds_read_b128 v[184:187], v200 offset:512
	s_waitcnt vmcnt(60)
	v_cndmask_b32_e64 v192, v101, v100, vcc
	v_cndmask_b32_e64 v193, v103, v102, vcc
	v_cndmask_b32_e64 v194, v105, v104, vcc
	v_cndmask_b32_e64 v195, v107, v106, vcc
	v_mov_b32_dpp v196, v192 quad_perm:[1,0,3,2] row_mask:0xf bank_mask:0xf
	v_mov_b32_dpp v197, v193 quad_perm:[1,0,3,2] row_mask:0xf bank_mask:0xf
	v_mov_b32_dpp v198, v194 quad_perm:[1,0,3,2] row_mask:0xf bank_mask:0xf
	v_mov_b32_dpp v199, v195 quad_perm:[1,0,3,2] row_mask:0xf bank_mask:0xf
	v_cndmask_b32_e64 v100, v100, v196, vcc
	v_cndmask_b32_e64 v101, v196, v101, vcc
	v_cndmask_b32_e64 v102, v102, v197, vcc
	v_cndmask_b32_e64 v103, v197, v103, vcc
	v_cndmask_b32_e64 v104, v104, v198, vcc
	v_cndmask_b32_e64 v105, v198, v105, vcc
	v_cndmask_b32_e64 v106, v106, v199, vcc
	v_cndmask_b32_e64 v107, v199, v107, vcc
	v_cvt_pk_bf16_f32 v14, v100, v101
	v_cvt_pk_bf16_f32 v15, v102, v103
	v_cvt_pk_bf16_f32 v16, v104, v105
	v_cvt_pk_bf16_f32 v17, v106, v107
	v_lshlrev_b32_e32 v84, 16, v14
	v_and_b32_e32 v85, 0xffff0000, v14
	v_sub_f32_e32 v100, v100, v84
	v_sub_f32_e32 v101, v101, v85
	v_cvt_pk_bf16_f32 v188, v100, v101
	v_lshlrev_b32_e32 v84, 16, v15
	v_and_b32_e32 v85, 0xffff0000, v15
	v_sub_f32_e32 v102, v102, v84
	v_sub_f32_e32 v103, v103, v85
	v_cvt_pk_bf16_f32 v189, v102, v103
	v_lshlrev_b32_e32 v84, 16, v16
	v_and_b32_e32 v85, 0xffff0000, v16
	v_sub_f32_e32 v104, v104, v84
	v_sub_f32_e32 v105, v105, v85
	v_cvt_pk_bf16_f32 v190, v104, v105
	v_lshlrev_b32_e32 v84, 16, v17
	v_and_b32_e32 v85, 0xffff0000, v17
	v_sub_f32_e32 v106, v106, v84
	v_sub_f32_e32 v107, v107, v85
	v_cvt_pk_bf16_f32 v191, v106, v107
	global_load_dwordx2 v[100:101], v86, s[100:101]
	s_lshl_b32 s4, s40, 1
	s_add_u32 s100, s100, s4
	s_addc_u32 s101, s101, 0
	global_load_dwordx2 v[102:103], v86, s[100:101]
	s_lshl_b32 s4, s40, 1
	s_add_u32 s100, s100, s4
	s_addc_u32 s101, s101, 0
	global_load_dwordx2 v[104:105], v86, s[100:101]
	s_lshl_b32 s4, s40, 1
	s_add_u32 s100, s100, s4
	s_addc_u32 s101, s101, 0
	global_load_dwordx2 v[106:107], v86, s[100:101]
	s_mul_i32 s4, s40, 26
	s_add_u32 s100, s100, s4
	s_addc_u32 s101, s101, 0
	s_waitcnt lgkmcnt(0)
	v_mfma_f32_16x16x32_bf16 v[10:13], v[164:167], v[14:17], v[10:13]
	v_mfma_f32_16x16x32_bf16 v[6:9], v[172:175], v[14:17], v[6:9]
	v_mfma_f32_16x16x32_bf16 v[2:5], v[180:183], v[14:17], v[2:5]
	v_mfma_f32_16x16x32_bf16 v[10:13], v[164:167], v[188:191], v[10:13]
	ds_read_b128 v[164:167], v87 offset:576
	v_mfma_f32_16x16x32_bf16 v[6:9], v[172:175], v[188:191], v[6:9]
	ds_read_b128 v[172:175], v87 offset:33600
	v_mfma_f32_16x16x32_bf16 v[2:5], v[180:183], v[188:191], v[2:5]
	ds_read_b128 v[180:183], v89 offset:576
	v_mfma_f32_16x16x32_bf16 v[10:13], v[168:171], v[14:17], v[10:13]
	ds_read_b128 v[168:171], v88 offset:576
	v_mfma_f32_16x16x32_bf16 v[6:9], v[176:179], v[14:17], v[6:9]
	ds_read_b128 v[176:179], v88 offset:33600
	v_mfma_f32_16x16x32_bf16 v[2:5], v[184:187], v[14:17], v[2:5]
	ds_read_b128 v[184:187], v200 offset:576
	s_waitcnt vmcnt(60)
	v_cndmask_b32_e64 v192, v109, v108, vcc
	v_cndmask_b32_e64 v193, v111, v110, vcc
	v_cndmask_b32_e64 v194, v113, v112, vcc
	v_cndmask_b32_e64 v195, v115, v114, vcc
	v_mov_b32_dpp v196, v192 quad_perm:[1,0,3,2] row_mask:0xf bank_mask:0xf
	v_mov_b32_dpp v197, v193 quad_perm:[1,0,3,2] row_mask:0xf bank_mask:0xf
	v_mov_b32_dpp v198, v194 quad_perm:[1,0,3,2] row_mask:0xf bank_mask:0xf
	v_mov_b32_dpp v199, v195 quad_perm:[1,0,3,2] row_mask:0xf bank_mask:0xf
	v_cndmask_b32_e64 v108, v108, v196, vcc
	v_cndmask_b32_e64 v109, v196, v109, vcc
	v_cndmask_b32_e64 v110, v110, v197, vcc
	v_cndmask_b32_e64 v111, v197, v111, vcc
	v_cndmask_b32_e64 v112, v112, v198, vcc
	v_cndmask_b32_e64 v113, v198, v113, vcc
	v_cndmask_b32_e64 v114, v114, v199, vcc
	v_cndmask_b32_e64 v115, v199, v115, vcc
	v_cvt_pk_bf16_f32 v14, v108, v109
	v_cvt_pk_bf16_f32 v15, v110, v111
	v_cvt_pk_bf16_f32 v16, v112, v113
	v_cvt_pk_bf16_f32 v17, v114, v115
	v_lshlrev_b32_e32 v84, 16, v14
	v_and_b32_e32 v85, 0xffff0000, v14
	v_sub_f32_e32 v108, v108, v84
	v_sub_f32_e32 v109, v109, v85
	v_cvt_pk_bf16_f32 v188, v108, v109
	v_lshlrev_b32_e32 v84, 16, v15
	v_and_b32_e32 v85, 0xffff0000, v15
	v_sub_f32_e32 v110, v110, v84
	v_sub_f32_e32 v111, v111, v85
	v_cvt_pk_bf16_f32 v189, v110, v111
	v_lshlrev_b32_e32 v84, 16, v16
	v_and_b32_e32 v85, 0xffff0000, v16
	v_sub_f32_e32 v112, v112, v84
	v_sub_f32_e32 v113, v113, v85
	v_cvt_pk_bf16_f32 v190, v112, v113
	v_lshlrev_b32_e32 v84, 16, v17
	v_and_b32_e32 v85, 0xffff0000, v17
	v_sub_f32_e32 v114, v114, v84
	v_sub_f32_e32 v115, v115, v85
	v_cvt_pk_bf16_f32 v191, v114, v115
	global_load_dwordx2 v[108:109], v86, s[100:101]
	s_lshl_b32 s4, s40, 1
	s_add_u32 s100, s100, s4
	s_addc_u32 s101, s101, 0
	global_load_dwordx2 v[110:111], v86, s[100:101]
	s_lshl_b32 s4, s40, 1
	s_add_u32 s100, s100, s4
	s_addc_u32 s101, s101, 0
	global_load_dwordx2 v[112:113], v86, s[100:101]
	s_lshl_b32 s4, s40, 1
	s_add_u32 s100, s100, s4
	s_addc_u32 s101, s101, 0
	global_load_dwordx2 v[114:115], v86, s[100:101]
	s_mul_i32 s4, s40, 26
	s_add_u32 s100, s100, s4
	s_addc_u32 s101, s101, 0
	s_waitcnt lgkmcnt(0)
	v_mfma_f32_16x16x32_bf16 v[10:13], v[164:167], v[14:17], v[10:13]
	v_mfma_f32_16x16x32_bf16 v[6:9], v[172:175], v[14:17], v[6:9]
	v_mfma_f32_16x16x32_bf16 v[2:5], v[180:183], v[14:17], v[2:5]
	v_mfma_f32_16x16x32_bf16 v[10:13], v[164:167], v[188:191], v[10:13]
	ds_read_b128 v[164:167], v87 offset:640
	v_mfma_f32_16x16x32_bf16 v[6:9], v[172:175], v[188:191], v[6:9]
	ds_read_b128 v[172:175], v87 offset:33664
	v_mfma_f32_16x16x32_bf16 v[2:5], v[180:183], v[188:191], v[2:5]
	ds_read_b128 v[180:183], v89 offset:640
	v_mfma_f32_16x16x32_bf16 v[10:13], v[168:171], v[14:17], v[10:13]
	ds_read_b128 v[168:171], v88 offset:640
	v_mfma_f32_16x16x32_bf16 v[6:9], v[176:179], v[14:17], v[6:9]
	ds_read_b128 v[176:179], v88 offset:33664
	v_mfma_f32_16x16x32_bf16 v[2:5], v[184:187], v[14:17], v[2:5]
	ds_read_b128 v[184:187], v200 offset:640
	s_waitcnt vmcnt(60)
	v_cndmask_b32_e64 v192, v117, v116, vcc
	v_cndmask_b32_e64 v193, v119, v118, vcc
	v_cndmask_b32_e64 v194, v121, v120, vcc
	v_cndmask_b32_e64 v195, v123, v122, vcc
	v_mov_b32_dpp v196, v192 quad_perm:[1,0,3,2] row_mask:0xf bank_mask:0xf
	v_mov_b32_dpp v197, v193 quad_perm:[1,0,3,2] row_mask:0xf bank_mask:0xf
	v_mov_b32_dpp v198, v194 quad_perm:[1,0,3,2] row_mask:0xf bank_mask:0xf
	v_mov_b32_dpp v199, v195 quad_perm:[1,0,3,2] row_mask:0xf bank_mask:0xf
	v_cndmask_b32_e64 v116, v116, v196, vcc
	v_cndmask_b32_e64 v117, v196, v117, vcc
	v_cndmask_b32_e64 v118, v118, v197, vcc
	v_cndmask_b32_e64 v119, v197, v119, vcc
	v_cndmask_b32_e64 v120, v120, v198, vcc
	v_cndmask_b32_e64 v121, v198, v121, vcc
	v_cndmask_b32_e64 v122, v122, v199, vcc
	v_cndmask_b32_e64 v123, v199, v123, vcc
	v_cvt_pk_bf16_f32 v14, v116, v117
	v_cvt_pk_bf16_f32 v15, v118, v119
	v_cvt_pk_bf16_f32 v16, v120, v121
	v_cvt_pk_bf16_f32 v17, v122, v123
	v_lshlrev_b32_e32 v84, 16, v14
	v_and_b32_e32 v85, 0xffff0000, v14
	v_sub_f32_e32 v116, v116, v84
	v_sub_f32_e32 v117, v117, v85
	v_cvt_pk_bf16_f32 v188, v116, v117
	v_lshlrev_b32_e32 v84, 16, v15
	v_and_b32_e32 v85, 0xffff0000, v15
	v_sub_f32_e32 v118, v118, v84
	v_sub_f32_e32 v119, v119, v85
	v_cvt_pk_bf16_f32 v189, v118, v119
	v_lshlrev_b32_e32 v84, 16, v16
	v_and_b32_e32 v85, 0xffff0000, v16
	v_sub_f32_e32 v120, v120, v84
	v_sub_f32_e32 v121, v121, v85
	v_cvt_pk_bf16_f32 v190, v120, v121
	v_lshlrev_b32_e32 v84, 16, v17
	v_and_b32_e32 v85, 0xffff0000, v17
	v_sub_f32_e32 v122, v122, v84
	v_sub_f32_e32 v123, v123, v85
	v_cvt_pk_bf16_f32 v191, v122, v123
	global_load_dwordx2 v[116:117], v86, s[100:101]
	s_lshl_b32 s4, s40, 1
	s_add_u32 s100, s100, s4
	s_addc_u32 s101, s101, 0
	global_load_dwordx2 v[118:119], v86, s[100:101]
	s_lshl_b32 s4, s40, 1
	s_add_u32 s100, s100, s4
	s_addc_u32 s101, s101, 0
	global_load_dwordx2 v[120:121], v86, s[100:101]
	s_lshl_b32 s4, s40, 1
	s_add_u32 s100, s100, s4
	s_addc_u32 s101, s101, 0
	global_load_dwordx2 v[122:123], v86, s[100:101]
	s_mul_i32 s4, s40, 26
	s_add_u32 s100, s100, s4
	s_addc_u32 s101, s101, 0
	s_waitcnt lgkmcnt(0)
	v_mfma_f32_16x16x32_bf16 v[10:13], v[164:167], v[14:17], v[10:13]
	v_mfma_f32_16x16x32_bf16 v[6:9], v[172:175], v[14:17], v[6:9]
	v_mfma_f32_16x16x32_bf16 v[2:5], v[180:183], v[14:17], v[2:5]
	v_mfma_f32_16x16x32_bf16 v[10:13], v[164:167], v[188:191], v[10:13]
	ds_read_b128 v[164:167], v87 offset:704
	v_mfma_f32_16x16x32_bf16 v[6:9], v[172:175], v[188:191], v[6:9]
	ds_read_b128 v[172:175], v87 offset:33728
	v_mfma_f32_16x16x32_bf16 v[2:5], v[180:183], v[188:191], v[2:5]
	ds_read_b128 v[180:183], v89 offset:704
	v_mfma_f32_16x16x32_bf16 v[10:13], v[168:171], v[14:17], v[10:13]
	ds_read_b128 v[168:171], v88 offset:704
	v_mfma_f32_16x16x32_bf16 v[6:9], v[176:179], v[14:17], v[6:9]
	ds_read_b128 v[176:179], v88 offset:33728
	v_mfma_f32_16x16x32_bf16 v[2:5], v[184:187], v[14:17], v[2:5]
	ds_read_b128 v[184:187], v200 offset:704
	s_waitcnt vmcnt(60)
	v_cndmask_b32_e64 v192, v125, v124, vcc
	v_cndmask_b32_e64 v193, v127, v126, vcc
	v_cndmask_b32_e64 v194, v129, v128, vcc
	v_cndmask_b32_e64 v195, v131, v130, vcc
	v_mov_b32_dpp v196, v192 quad_perm:[1,0,3,2] row_mask:0xf bank_mask:0xf
	v_mov_b32_dpp v197, v193 quad_perm:[1,0,3,2] row_mask:0xf bank_mask:0xf
	v_mov_b32_dpp v198, v194 quad_perm:[1,0,3,2] row_mask:0xf bank_mask:0xf
	v_mov_b32_dpp v199, v195 quad_perm:[1,0,3,2] row_mask:0xf bank_mask:0xf
	v_cndmask_b32_e64 v124, v124, v196, vcc
	v_cndmask_b32_e64 v125, v196, v125, vcc
	v_cndmask_b32_e64 v126, v126, v197, vcc
	v_cndmask_b32_e64 v127, v197, v127, vcc
	v_cndmask_b32_e64 v128, v128, v198, vcc
	v_cndmask_b32_e64 v129, v198, v129, vcc
	v_cndmask_b32_e64 v130, v130, v199, vcc
	v_cndmask_b32_e64 v131, v199, v131, vcc
	v_cvt_pk_bf16_f32 v14, v124, v125
	v_cvt_pk_bf16_f32 v15, v126, v127
	v_cvt_pk_bf16_f32 v16, v128, v129
	v_cvt_pk_bf16_f32 v17, v130, v131
	v_lshlrev_b32_e32 v84, 16, v14
	v_and_b32_e32 v85, 0xffff0000, v14
	v_sub_f32_e32 v124, v124, v84
	v_sub_f32_e32 v125, v125, v85
	v_cvt_pk_bf16_f32 v188, v124, v125
	v_lshlrev_b32_e32 v84, 16, v15
	v_and_b32_e32 v85, 0xffff0000, v15
	v_sub_f32_e32 v126, v126, v84
	v_sub_f32_e32 v127, v127, v85
	v_cvt_pk_bf16_f32 v189, v126, v127
	v_lshlrev_b32_e32 v84, 16, v16
	v_and_b32_e32 v85, 0xffff0000, v16
	v_sub_f32_e32 v128, v128, v84
	v_sub_f32_e32 v129, v129, v85
	v_cvt_pk_bf16_f32 v190, v128, v129
	v_lshlrev_b32_e32 v84, 16, v17
	v_and_b32_e32 v85, 0xffff0000, v17
	v_sub_f32_e32 v130, v130, v84
	v_sub_f32_e32 v131, v131, v85
	v_cvt_pk_bf16_f32 v191, v130, v131
	global_load_dwordx2 v[124:125], v86, s[100:101]
	s_lshl_b32 s4, s40, 1
	s_add_u32 s100, s100, s4
	s_addc_u32 s101, s101, 0
	global_load_dwordx2 v[126:127], v86, s[100:101]
	s_lshl_b32 s4, s40, 1
	s_add_u32 s100, s100, s4
	s_addc_u32 s101, s101, 0
	global_load_dwordx2 v[128:129], v86, s[100:101]
	s_lshl_b32 s4, s40, 1
	s_add_u32 s100, s100, s4
	s_addc_u32 s101, s101, 0
	global_load_dwordx2 v[130:131], v86, s[100:101]
	s_mul_i32 s4, s40, 26
	s_add_u32 s100, s100, s4
	s_addc_u32 s101, s101, 0
	s_waitcnt lgkmcnt(0)
	v_mfma_f32_16x16x32_bf16 v[10:13], v[164:167], v[14:17], v[10:13]
	v_mfma_f32_16x16x32_bf16 v[6:9], v[172:175], v[14:17], v[6:9]
	v_mfma_f32_16x16x32_bf16 v[2:5], v[180:183], v[14:17], v[2:5]
	v_mfma_f32_16x16x32_bf16 v[10:13], v[164:167], v[188:191], v[10:13]
	ds_read_b128 v[164:167], v87 offset:768
	v_mfma_f32_16x16x32_bf16 v[6:9], v[172:175], v[188:191], v[6:9]
	ds_read_b128 v[172:175], v87 offset:33792
	v_mfma_f32_16x16x32_bf16 v[2:5], v[180:183], v[188:191], v[2:5]
	ds_read_b128 v[180:183], v89 offset:768
	v_mfma_f32_16x16x32_bf16 v[10:13], v[168:171], v[14:17], v[10:13]
	ds_read_b128 v[168:171], v88 offset:768
	v_mfma_f32_16x16x32_bf16 v[6:9], v[176:179], v[14:17], v[6:9]
	ds_read_b128 v[176:179], v88 offset:33792
	v_mfma_f32_16x16x32_bf16 v[2:5], v[184:187], v[14:17], v[2:5]
	ds_read_b128 v[184:187], v200 offset:768
	s_waitcnt vmcnt(60)
	v_cndmask_b32_e64 v192, v133, v132, vcc
	v_cndmask_b32_e64 v193, v135, v134, vcc
	v_cndmask_b32_e64 v194, v137, v136, vcc
	v_cndmask_b32_e64 v195, v139, v138, vcc
	v_mov_b32_dpp v196, v192 quad_perm:[1,0,3,2] row_mask:0xf bank_mask:0xf
	v_mov_b32_dpp v197, v193 quad_perm:[1,0,3,2] row_mask:0xf bank_mask:0xf
	v_mov_b32_dpp v198, v194 quad_perm:[1,0,3,2] row_mask:0xf bank_mask:0xf
	v_mov_b32_dpp v199, v195 quad_perm:[1,0,3,2] row_mask:0xf bank_mask:0xf
	v_cndmask_b32_e64 v132, v132, v196, vcc
	v_cndmask_b32_e64 v133, v196, v133, vcc
	v_cndmask_b32_e64 v134, v134, v197, vcc
	v_cndmask_b32_e64 v135, v197, v135, vcc
	v_cndmask_b32_e64 v136, v136, v198, vcc
	v_cndmask_b32_e64 v137, v198, v137, vcc
	v_cndmask_b32_e64 v138, v138, v199, vcc
	v_cndmask_b32_e64 v139, v199, v139, vcc
	v_cvt_pk_bf16_f32 v14, v132, v133
	v_cvt_pk_bf16_f32 v15, v134, v135
	v_cvt_pk_bf16_f32 v16, v136, v137
	v_cvt_pk_bf16_f32 v17, v138, v139
	v_lshlrev_b32_e32 v84, 16, v14
	v_and_b32_e32 v85, 0xffff0000, v14
	v_sub_f32_e32 v132, v132, v84
	v_sub_f32_e32 v133, v133, v85
	v_cvt_pk_bf16_f32 v188, v132, v133
	v_lshlrev_b32_e32 v84, 16, v15
	v_and_b32_e32 v85, 0xffff0000, v15
	v_sub_f32_e32 v134, v134, v84
	v_sub_f32_e32 v135, v135, v85
	v_cvt_pk_bf16_f32 v189, v134, v135
	v_lshlrev_b32_e32 v84, 16, v16
	v_and_b32_e32 v85, 0xffff0000, v16
	v_sub_f32_e32 v136, v136, v84
	v_sub_f32_e32 v137, v137, v85
	v_cvt_pk_bf16_f32 v190, v136, v137
	v_lshlrev_b32_e32 v84, 16, v17
	v_and_b32_e32 v85, 0xffff0000, v17
	v_sub_f32_e32 v138, v138, v84
	v_sub_f32_e32 v139, v139, v85
	v_cvt_pk_bf16_f32 v191, v138, v139
	global_load_dwordx2 v[132:133], v86, s[100:101]
	s_lshl_b32 s4, s40, 1
	s_add_u32 s100, s100, s4
	s_addc_u32 s101, s101, 0
	global_load_dwordx2 v[134:135], v86, s[100:101]
	s_lshl_b32 s4, s40, 1
	s_add_u32 s100, s100, s4
	s_addc_u32 s101, s101, 0
	global_load_dwordx2 v[136:137], v86, s[100:101]
	s_lshl_b32 s4, s40, 1
	s_add_u32 s100, s100, s4
	s_addc_u32 s101, s101, 0
	global_load_dwordx2 v[138:139], v86, s[100:101]
	s_mul_i32 s4, s40, 26
	s_add_u32 s100, s100, s4
	s_addc_u32 s101, s101, 0
	s_waitcnt lgkmcnt(0)
	v_mfma_f32_16x16x32_bf16 v[10:13], v[164:167], v[14:17], v[10:13]
	v_mfma_f32_16x16x32_bf16 v[6:9], v[172:175], v[14:17], v[6:9]
	v_mfma_f32_16x16x32_bf16 v[2:5], v[180:183], v[14:17], v[2:5]
	v_mfma_f32_16x16x32_bf16 v[10:13], v[164:167], v[188:191], v[10:13]
	ds_read_b128 v[164:167], v87 offset:832
	v_mfma_f32_16x16x32_bf16 v[6:9], v[172:175], v[188:191], v[6:9]
	ds_read_b128 v[172:175], v87 offset:33856
	v_mfma_f32_16x16x32_bf16 v[2:5], v[180:183], v[188:191], v[2:5]
	ds_read_b128 v[180:183], v89 offset:832
	v_mfma_f32_16x16x32_bf16 v[10:13], v[168:171], v[14:17], v[10:13]
	ds_read_b128 v[168:171], v88 offset:832
	v_mfma_f32_16x16x32_bf16 v[6:9], v[176:179], v[14:17], v[6:9]
	ds_read_b128 v[176:179], v88 offset:33856
	v_mfma_f32_16x16x32_bf16 v[2:5], v[184:187], v[14:17], v[2:5]
	ds_read_b128 v[184:187], v200 offset:832
	s_waitcnt vmcnt(60)
	v_cndmask_b32_e64 v192, v141, v140, vcc
	v_cndmask_b32_e64 v193, v143, v142, vcc
	v_cndmask_b32_e64 v194, v145, v144, vcc
	v_cndmask_b32_e64 v195, v147, v146, vcc
	v_mov_b32_dpp v196, v192 quad_perm:[1,0,3,2] row_mask:0xf bank_mask:0xf
	v_mov_b32_dpp v197, v193 quad_perm:[1,0,3,2] row_mask:0xf bank_mask:0xf
	v_mov_b32_dpp v198, v194 quad_perm:[1,0,3,2] row_mask:0xf bank_mask:0xf
	v_mov_b32_dpp v199, v195 quad_perm:[1,0,3,2] row_mask:0xf bank_mask:0xf
	v_cndmask_b32_e64 v140, v140, v196, vcc
	v_cndmask_b32_e64 v141, v196, v141, vcc
	v_cndmask_b32_e64 v142, v142, v197, vcc
	v_cndmask_b32_e64 v143, v197, v143, vcc
	v_cndmask_b32_e64 v144, v144, v198, vcc
	v_cndmask_b32_e64 v145, v198, v145, vcc
	v_cndmask_b32_e64 v146, v146, v199, vcc
	v_cndmask_b32_e64 v147, v199, v147, vcc
	v_cvt_pk_bf16_f32 v14, v140, v141
	v_cvt_pk_bf16_f32 v15, v142, v143
	v_cvt_pk_bf16_f32 v16, v144, v145
	v_cvt_pk_bf16_f32 v17, v146, v147
	v_lshlrev_b32_e32 v84, 16, v14
	v_and_b32_e32 v85, 0xffff0000, v14
	v_sub_f32_e32 v140, v140, v84
	v_sub_f32_e32 v141, v141, v85
	v_cvt_pk_bf16_f32 v188, v140, v141
	v_lshlrev_b32_e32 v84, 16, v15
	v_and_b32_e32 v85, 0xffff0000, v15
	v_sub_f32_e32 v142, v142, v84
	v_sub_f32_e32 v143, v143, v85
	v_cvt_pk_bf16_f32 v189, v142, v143
	v_lshlrev_b32_e32 v84, 16, v16
	v_and_b32_e32 v85, 0xffff0000, v16
	v_sub_f32_e32 v144, v144, v84
	v_sub_f32_e32 v145, v145, v85
	v_cvt_pk_bf16_f32 v190, v144, v145
	v_lshlrev_b32_e32 v84, 16, v17
	v_and_b32_e32 v85, 0xffff0000, v17
	v_sub_f32_e32 v146, v146, v84
	v_sub_f32_e32 v147, v147, v85
	v_cvt_pk_bf16_f32 v191, v146, v147
	global_load_dwordx2 v[140:141], v86, s[100:101]
	s_lshl_b32 s4, s40, 1
	s_add_u32 s100, s100, s4
	s_addc_u32 s101, s101, 0
	global_load_dwordx2 v[142:143], v86, s[100:101]
	s_lshl_b32 s4, s40, 1
	s_add_u32 s100, s100, s4
	s_addc_u32 s101, s101, 0
	global_load_dwordx2 v[144:145], v86, s[100:101]
	s_lshl_b32 s4, s40, 1
	s_add_u32 s100, s100, s4
	s_addc_u32 s101, s101, 0
	global_load_dwordx2 v[146:147], v86, s[100:101]
	s_mul_i32 s4, s40, 26
	s_add_u32 s100, s100, s4
	s_addc_u32 s101, s101, 0
	s_waitcnt lgkmcnt(0)
	v_mfma_f32_16x16x32_bf16 v[10:13], v[164:167], v[14:17], v[10:13]
	v_mfma_f32_16x16x32_bf16 v[6:9], v[172:175], v[14:17], v[6:9]
	v_mfma_f32_16x16x32_bf16 v[2:5], v[180:183], v[14:17], v[2:5]
	v_mfma_f32_16x16x32_bf16 v[10:13], v[164:167], v[188:191], v[10:13]
	ds_read_b128 v[164:167], v87 offset:896
	v_mfma_f32_16x16x32_bf16 v[6:9], v[172:175], v[188:191], v[6:9]
	ds_read_b128 v[172:175], v87 offset:33920
	v_mfma_f32_16x16x32_bf16 v[2:5], v[180:183], v[188:191], v[2:5]
	ds_read_b128 v[180:183], v89 offset:896
	v_mfma_f32_16x16x32_bf16 v[10:13], v[168:171], v[14:17], v[10:13]
	ds_read_b128 v[168:171], v88 offset:896
	v_mfma_f32_16x16x32_bf16 v[6:9], v[176:179], v[14:17], v[6:9]
	ds_read_b128 v[176:179], v88 offset:33920
	v_mfma_f32_16x16x32_bf16 v[2:5], v[184:187], v[14:17], v[2:5]
	ds_read_b128 v[184:187], v200 offset:896
	s_waitcnt vmcnt(60)
	v_cndmask_b32_e64 v192, v149, v148, vcc
	v_cndmask_b32_e64 v193, v151, v150, vcc
	v_cndmask_b32_e64 v194, v153, v152, vcc
	v_cndmask_b32_e64 v195, v155, v154, vcc
	v_mov_b32_dpp v196, v192 quad_perm:[1,0,3,2] row_mask:0xf bank_mask:0xf
	v_mov_b32_dpp v197, v193 quad_perm:[1,0,3,2] row_mask:0xf bank_mask:0xf
	v_mov_b32_dpp v198, v194 quad_perm:[1,0,3,2] row_mask:0xf bank_mask:0xf
	v_mov_b32_dpp v199, v195 quad_perm:[1,0,3,2] row_mask:0xf bank_mask:0xf
	v_cndmask_b32_e64 v148, v148, v196, vcc
	v_cndmask_b32_e64 v149, v196, v149, vcc
	v_cndmask_b32_e64 v150, v150, v197, vcc
	v_cndmask_b32_e64 v151, v197, v151, vcc
	v_cndmask_b32_e64 v152, v152, v198, vcc
	v_cndmask_b32_e64 v153, v198, v153, vcc
	v_cndmask_b32_e64 v154, v154, v199, vcc
	v_cndmask_b32_e64 v155, v199, v155, vcc
	v_cvt_pk_bf16_f32 v14, v148, v149
	v_cvt_pk_bf16_f32 v15, v150, v151
	v_cvt_pk_bf16_f32 v16, v152, v153
	v_cvt_pk_bf16_f32 v17, v154, v155
	v_lshlrev_b32_e32 v84, 16, v14
	v_and_b32_e32 v85, 0xffff0000, v14
	v_sub_f32_e32 v148, v148, v84
	v_sub_f32_e32 v149, v149, v85
	v_cvt_pk_bf16_f32 v188, v148, v149
	v_lshlrev_b32_e32 v84, 16, v15
	v_and_b32_e32 v85, 0xffff0000, v15
	v_sub_f32_e32 v150, v150, v84
	v_sub_f32_e32 v151, v151, v85
	v_cvt_pk_bf16_f32 v189, v150, v151
	v_lshlrev_b32_e32 v84, 16, v16
	v_and_b32_e32 v85, 0xffff0000, v16
	v_sub_f32_e32 v152, v152, v84
	v_sub_f32_e32 v153, v153, v85
	v_cvt_pk_bf16_f32 v190, v152, v153
	v_lshlrev_b32_e32 v84, 16, v17
	v_and_b32_e32 v85, 0xffff0000, v17
	v_sub_f32_e32 v154, v154, v84
	v_sub_f32_e32 v155, v155, v85
	v_cvt_pk_bf16_f32 v191, v154, v155
	global_load_dwordx2 v[148:149], v86, s[100:101]
	s_lshl_b32 s4, s40, 1
	s_add_u32 s100, s100, s4
	s_addc_u32 s101, s101, 0
	global_load_dwordx2 v[150:151], v86, s[100:101]
	s_lshl_b32 s4, s40, 1
	s_add_u32 s100, s100, s4
	s_addc_u32 s101, s101, 0
	global_load_dwordx2 v[152:153], v86, s[100:101]
	s_lshl_b32 s4, s40, 1
	s_add_u32 s100, s100, s4
	s_addc_u32 s101, s101, 0
	global_load_dwordx2 v[154:155], v86, s[100:101]
	s_mul_i32 s4, s40, 26
	s_add_u32 s100, s100, s4
	s_addc_u32 s101, s101, 0
	s_waitcnt lgkmcnt(0)
	v_mfma_f32_16x16x32_bf16 v[10:13], v[164:167], v[14:17], v[10:13]
	v_mfma_f32_16x16x32_bf16 v[6:9], v[172:175], v[14:17], v[6:9]
	v_mfma_f32_16x16x32_bf16 v[2:5], v[180:183], v[14:17], v[2:5]
	v_mfma_f32_16x16x32_bf16 v[10:13], v[164:167], v[188:191], v[10:13]
	ds_read_b128 v[164:167], v87 offset:960
	v_mfma_f32_16x16x32_bf16 v[6:9], v[172:175], v[188:191], v[6:9]
	ds_read_b128 v[172:175], v87 offset:33984
	v_mfma_f32_16x16x32_bf16 v[2:5], v[180:183], v[188:191], v[2:5]
	ds_read_b128 v[180:183], v89 offset:960
	v_mfma_f32_16x16x32_bf16 v[10:13], v[168:171], v[14:17], v[10:13]
	ds_read_b128 v[168:171], v88 offset:960
	v_mfma_f32_16x16x32_bf16 v[6:9], v[176:179], v[14:17], v[6:9]
	ds_read_b128 v[176:179], v88 offset:33984
	v_mfma_f32_16x16x32_bf16 v[2:5], v[184:187], v[14:17], v[2:5]
	ds_read_b128 v[184:187], v200 offset:960
	s_waitcnt vmcnt(60)
	v_cndmask_b32_e64 v192, v157, v156, vcc
	v_cndmask_b32_e64 v193, v159, v158, vcc
	v_cndmask_b32_e64 v194, v161, v160, vcc
	v_cndmask_b32_e64 v195, v163, v162, vcc
	v_mov_b32_dpp v196, v192 quad_perm:[1,0,3,2] row_mask:0xf bank_mask:0xf
	v_mov_b32_dpp v197, v193 quad_perm:[1,0,3,2] row_mask:0xf bank_mask:0xf
	v_mov_b32_dpp v198, v194 quad_perm:[1,0,3,2] row_mask:0xf bank_mask:0xf
	v_mov_b32_dpp v199, v195 quad_perm:[1,0,3,2] row_mask:0xf bank_mask:0xf
	v_cndmask_b32_e64 v156, v156, v196, vcc
	v_cndmask_b32_e64 v157, v196, v157, vcc
	v_cndmask_b32_e64 v158, v158, v197, vcc
	v_cndmask_b32_e64 v159, v197, v159, vcc
	v_cndmask_b32_e64 v160, v160, v198, vcc
	v_cndmask_b32_e64 v161, v198, v161, vcc
	v_cndmask_b32_e64 v162, v162, v199, vcc
	v_cndmask_b32_e64 v163, v199, v163, vcc
	v_cvt_pk_bf16_f32 v14, v156, v157
	v_cvt_pk_bf16_f32 v15, v158, v159
	v_cvt_pk_bf16_f32 v16, v160, v161
	v_cvt_pk_bf16_f32 v17, v162, v163
	v_lshlrev_b32_e32 v84, 16, v14
	v_and_b32_e32 v85, 0xffff0000, v14
	v_sub_f32_e32 v156, v156, v84
	v_sub_f32_e32 v157, v157, v85
	v_cvt_pk_bf16_f32 v188, v156, v157
	v_lshlrev_b32_e32 v84, 16, v15
	v_and_b32_e32 v85, 0xffff0000, v15
	v_sub_f32_e32 v158, v158, v84
	v_sub_f32_e32 v159, v159, v85
	v_cvt_pk_bf16_f32 v189, v158, v159
	v_lshlrev_b32_e32 v84, 16, v16
	v_and_b32_e32 v85, 0xffff0000, v16
	v_sub_f32_e32 v160, v160, v84
	v_sub_f32_e32 v161, v161, v85
	v_cvt_pk_bf16_f32 v190, v160, v161
	v_lshlrev_b32_e32 v84, 16, v17
	v_and_b32_e32 v85, 0xffff0000, v17
	v_sub_f32_e32 v162, v162, v84
	v_sub_f32_e32 v163, v163, v85
	v_cvt_pk_bf16_f32 v191, v162, v163
	global_load_dwordx2 v[156:157], v86, s[100:101]
	s_lshl_b32 s4, s40, 1
	s_add_u32 s100, s100, s4
	s_addc_u32 s101, s101, 0
	global_load_dwordx2 v[158:159], v86, s[100:101]
	s_lshl_b32 s4, s40, 1
	s_add_u32 s100, s100, s4
	s_addc_u32 s101, s101, 0
	global_load_dwordx2 v[160:161], v86, s[100:101]
	s_lshl_b32 s4, s40, 1
	s_add_u32 s100, s100, s4
	s_addc_u32 s101, s101, 0
	global_load_dwordx2 v[162:163], v86, s[100:101]
	s_mul_i32 s4, s40, 26
	s_add_u32 s100, s100, s4
	s_addc_u32 s101, s101, 0
	s_waitcnt lgkmcnt(0)
	v_mfma_f32_16x16x32_bf16 v[10:13], v[164:167], v[14:17], v[10:13]
	v_mfma_f32_16x16x32_bf16 v[6:9], v[172:175], v[14:17], v[6:9]
	v_mfma_f32_16x16x32_bf16 v[2:5], v[180:183], v[14:17], v[2:5]
	v_mfma_f32_16x16x32_bf16 v[10:13], v[164:167], v[188:191], v[10:13]
	ds_read_b128 v[164:167], v87 offset:1024
	v_mfma_f32_16x16x32_bf16 v[6:9], v[172:175], v[188:191], v[6:9]
	ds_read_b128 v[172:175], v87 offset:34048
	v_mfma_f32_16x16x32_bf16 v[2:5], v[180:183], v[188:191], v[2:5]
	ds_read_b128 v[180:183], v89 offset:1024
	v_mfma_f32_16x16x32_bf16 v[10:13], v[168:171], v[14:17], v[10:13]
	ds_read_b128 v[168:171], v88 offset:1024
	v_mfma_f32_16x16x32_bf16 v[6:9], v[176:179], v[14:17], v[6:9]
	ds_read_b128 v[176:179], v88 offset:34048
	v_mfma_f32_16x16x32_bf16 v[2:5], v[184:187], v[14:17], v[2:5]
	ds_read_b128 v[184:187], v200 offset:1024
	s_waitcnt vmcnt(60)
	v_cndmask_b32_e64 v192, v27, v26, vcc
	v_cndmask_b32_e64 v193, v29, v28, vcc
	v_cndmask_b32_e64 v194, v31, v30, vcc
	v_cndmask_b32_e64 v195, v33, v32, vcc
	v_mov_b32_dpp v196, v192 quad_perm:[1,0,3,2] row_mask:0xf bank_mask:0xf
	v_mov_b32_dpp v197, v193 quad_perm:[1,0,3,2] row_mask:0xf bank_mask:0xf
	v_mov_b32_dpp v198, v194 quad_perm:[1,0,3,2] row_mask:0xf bank_mask:0xf
	v_mov_b32_dpp v199, v195 quad_perm:[1,0,3,2] row_mask:0xf bank_mask:0xf
	v_cndmask_b32_e64 v26, v26, v196, vcc
	v_cndmask_b32_e64 v27, v196, v27, vcc
	v_cndmask_b32_e64 v28, v28, v197, vcc
	v_cndmask_b32_e64 v29, v197, v29, vcc
	v_cndmask_b32_e64 v30, v30, v198, vcc
	v_cndmask_b32_e64 v31, v198, v31, vcc
	v_cndmask_b32_e64 v32, v32, v199, vcc
	v_cndmask_b32_e64 v33, v199, v33, vcc
	v_cvt_pk_bf16_f32 v14, v26, v27
	v_cvt_pk_bf16_f32 v15, v28, v29
	v_cvt_pk_bf16_f32 v16, v30, v31
	v_cvt_pk_bf16_f32 v17, v32, v33
	v_lshlrev_b32_e32 v84, 16, v14
	v_and_b32_e32 v85, 0xffff0000, v14
	v_sub_f32_e32 v26, v26, v84
	v_sub_f32_e32 v27, v27, v85
	v_cvt_pk_bf16_f32 v188, v26, v27
	v_lshlrev_b32_e32 v84, 16, v15
	v_and_b32_e32 v85, 0xffff0000, v15
	v_sub_f32_e32 v28, v28, v84
	v_sub_f32_e32 v29, v29, v85
	v_cvt_pk_bf16_f32 v189, v28, v29
	v_lshlrev_b32_e32 v84, 16, v16
	v_and_b32_e32 v85, 0xffff0000, v16
	v_sub_f32_e32 v30, v30, v84
	v_sub_f32_e32 v31, v31, v85
	v_cvt_pk_bf16_f32 v190, v30, v31
	v_lshlrev_b32_e32 v84, 16, v17
	v_and_b32_e32 v85, 0xffff0000, v17
	v_sub_f32_e32 v32, v32, v84
	v_sub_f32_e32 v33, v33, v85
	v_cvt_pk_bf16_f32 v191, v32, v33
	s_waitcnt lgkmcnt(0)
	v_mfma_f32_16x16x32_bf16 v[10:13], v[164:167], v[14:17], v[10:13]
	v_mfma_f32_16x16x32_bf16 v[6:9], v[172:175], v[14:17], v[6:9]
	v_mfma_f32_16x16x32_bf16 v[2:5], v[180:183], v[14:17], v[2:5]
	v_mfma_f32_16x16x32_bf16 v[10:13], v[164:167], v[188:191], v[10:13]
	ds_read_b128 v[164:167], v87 offset:1088
	v_mfma_f32_16x16x32_bf16 v[6:9], v[172:175], v[188:191], v[6:9]
	ds_read_b128 v[172:175], v87 offset:34112
	v_mfma_f32_16x16x32_bf16 v[2:5], v[180:183], v[188:191], v[2:5]
	ds_read_b128 v[180:183], v89 offset:1088
	v_mfma_f32_16x16x32_bf16 v[10:13], v[168:171], v[14:17], v[10:13]
	ds_read_b128 v[168:171], v88 offset:1088
	v_mfma_f32_16x16x32_bf16 v[6:9], v[176:179], v[14:17], v[6:9]
	ds_read_b128 v[176:179], v88 offset:34112
	v_mfma_f32_16x16x32_bf16 v[2:5], v[184:187], v[14:17], v[2:5]
	ds_read_b128 v[184:187], v200 offset:1088
	s_waitcnt vmcnt(56)
	v_cndmask_b32_e64 v192, v35, v34, vcc
	v_cndmask_b32_e64 v193, v37, v36, vcc
	v_cndmask_b32_e64 v194, v39, v38, vcc
	v_cndmask_b32_e64 v195, v41, v40, vcc
	v_mov_b32_dpp v196, v192 quad_perm:[1,0,3,2] row_mask:0xf bank_mask:0xf
	v_mov_b32_dpp v197, v193 quad_perm:[1,0,3,2] row_mask:0xf bank_mask:0xf
	v_mov_b32_dpp v198, v194 quad_perm:[1,0,3,2] row_mask:0xf bank_mask:0xf
	v_mov_b32_dpp v199, v195 quad_perm:[1,0,3,2] row_mask:0xf bank_mask:0xf
	v_cndmask_b32_e64 v34, v34, v196, vcc
	v_cndmask_b32_e64 v35, v196, v35, vcc
	v_cndmask_b32_e64 v36, v36, v197, vcc
	v_cndmask_b32_e64 v37, v197, v37, vcc
	v_cndmask_b32_e64 v38, v38, v198, vcc
	v_cndmask_b32_e64 v39, v198, v39, vcc
	v_cndmask_b32_e64 v40, v40, v199, vcc
	v_cndmask_b32_e64 v41, v199, v41, vcc
	v_cvt_pk_bf16_f32 v14, v34, v35
	v_cvt_pk_bf16_f32 v15, v36, v37
	v_cvt_pk_bf16_f32 v16, v38, v39
	v_cvt_pk_bf16_f32 v17, v40, v41
	v_lshlrev_b32_e32 v84, 16, v14
	v_and_b32_e32 v85, 0xffff0000, v14
	v_sub_f32_e32 v34, v34, v84
	v_sub_f32_e32 v35, v35, v85
	v_cvt_pk_bf16_f32 v188, v34, v35
	v_lshlrev_b32_e32 v84, 16, v15
	v_and_b32_e32 v85, 0xffff0000, v15
	v_sub_f32_e32 v36, v36, v84
	v_sub_f32_e32 v37, v37, v85
	v_cvt_pk_bf16_f32 v189, v36, v37
	v_lshlrev_b32_e32 v84, 16, v16
	v_and_b32_e32 v85, 0xffff0000, v16
	v_sub_f32_e32 v38, v38, v84
	v_sub_f32_e32 v39, v39, v85
	v_cvt_pk_bf16_f32 v190, v38, v39
	v_lshlrev_b32_e32 v84, 16, v17
	v_and_b32_e32 v85, 0xffff0000, v17
	v_sub_f32_e32 v40, v40, v84
	v_sub_f32_e32 v41, v41, v85
	v_cvt_pk_bf16_f32 v191, v40, v41
	s_waitcnt lgkmcnt(0)
	v_mfma_f32_16x16x32_bf16 v[10:13], v[164:167], v[14:17], v[10:13]
	v_mfma_f32_16x16x32_bf16 v[6:9], v[172:175], v[14:17], v[6:9]
	v_mfma_f32_16x16x32_bf16 v[2:5], v[180:183], v[14:17], v[2:5]
	v_mfma_f32_16x16x32_bf16 v[10:13], v[164:167], v[188:191], v[10:13]
	ds_read_b128 v[164:167], v87 offset:1152
	v_mfma_f32_16x16x32_bf16 v[6:9], v[172:175], v[188:191], v[6:9]
	ds_read_b128 v[172:175], v87 offset:34176
	v_mfma_f32_16x16x32_bf16 v[2:5], v[180:183], v[188:191], v[2:5]
	ds_read_b128 v[180:183], v89 offset:1152
	v_mfma_f32_16x16x32_bf16 v[10:13], v[168:171], v[14:17], v[10:13]
	ds_read_b128 v[168:171], v88 offset:1152
	v_mfma_f32_16x16x32_bf16 v[6:9], v[176:179], v[14:17], v[6:9]
	ds_read_b128 v[176:179], v88 offset:34176
	v_mfma_f32_16x16x32_bf16 v[2:5], v[184:187], v[14:17], v[2:5]
	ds_read_b128 v[184:187], v200 offset:1152
	s_waitcnt vmcnt(52)
	v_cndmask_b32_e64 v192, v43, v42, vcc
	v_cndmask_b32_e64 v193, v45, v44, vcc
	v_cndmask_b32_e64 v194, v47, v46, vcc
	v_cndmask_b32_e64 v195, v49, v48, vcc
	v_mov_b32_dpp v196, v192 quad_perm:[1,0,3,2] row_mask:0xf bank_mask:0xf
	v_mov_b32_dpp v197, v193 quad_perm:[1,0,3,2] row_mask:0xf bank_mask:0xf
	v_mov_b32_dpp v198, v194 quad_perm:[1,0,3,2] row_mask:0xf bank_mask:0xf
	v_mov_b32_dpp v199, v195 quad_perm:[1,0,3,2] row_mask:0xf bank_mask:0xf
	v_cndmask_b32_e64 v42, v42, v196, vcc
	v_cndmask_b32_e64 v43, v196, v43, vcc
	v_cndmask_b32_e64 v44, v44, v197, vcc
	v_cndmask_b32_e64 v45, v197, v45, vcc
	v_cndmask_b32_e64 v46, v46, v198, vcc
	v_cndmask_b32_e64 v47, v198, v47, vcc
	v_cndmask_b32_e64 v48, v48, v199, vcc
	v_cndmask_b32_e64 v49, v199, v49, vcc
	v_cvt_pk_bf16_f32 v14, v42, v43
	v_cvt_pk_bf16_f32 v15, v44, v45
	v_cvt_pk_bf16_f32 v16, v46, v47
	v_cvt_pk_bf16_f32 v17, v48, v49
	v_lshlrev_b32_e32 v84, 16, v14
	v_and_b32_e32 v85, 0xffff0000, v14
	v_sub_f32_e32 v42, v42, v84
	v_sub_f32_e32 v43, v43, v85
	v_cvt_pk_bf16_f32 v188, v42, v43
	v_lshlrev_b32_e32 v84, 16, v15
	v_and_b32_e32 v85, 0xffff0000, v15
	v_sub_f32_e32 v44, v44, v84
	v_sub_f32_e32 v45, v45, v85
	v_cvt_pk_bf16_f32 v189, v44, v45
	v_lshlrev_b32_e32 v84, 16, v16
	v_and_b32_e32 v85, 0xffff0000, v16
	v_sub_f32_e32 v46, v46, v84
	v_sub_f32_e32 v47, v47, v85
	v_cvt_pk_bf16_f32 v190, v46, v47
	v_lshlrev_b32_e32 v84, 16, v17
	v_and_b32_e32 v85, 0xffff0000, v17
	v_sub_f32_e32 v48, v48, v84
	v_sub_f32_e32 v49, v49, v85
	v_cvt_pk_bf16_f32 v191, v48, v49
	s_waitcnt lgkmcnt(0)
	v_mfma_f32_16x16x32_bf16 v[10:13], v[164:167], v[14:17], v[10:13]
	v_mfma_f32_16x16x32_bf16 v[6:9], v[172:175], v[14:17], v[6:9]
	v_mfma_f32_16x16x32_bf16 v[2:5], v[180:183], v[14:17], v[2:5]
	v_mfma_f32_16x16x32_bf16 v[10:13], v[164:167], v[188:191], v[10:13]
	ds_read_b128 v[164:167], v87 offset:1216
	v_mfma_f32_16x16x32_bf16 v[6:9], v[172:175], v[188:191], v[6:9]
	ds_read_b128 v[172:175], v87 offset:34240
	v_mfma_f32_16x16x32_bf16 v[2:5], v[180:183], v[188:191], v[2:5]
	ds_read_b128 v[180:183], v89 offset:1216
	v_mfma_f32_16x16x32_bf16 v[10:13], v[168:171], v[14:17], v[10:13]
	ds_read_b128 v[168:171], v88 offset:1216
	v_mfma_f32_16x16x32_bf16 v[6:9], v[176:179], v[14:17], v[6:9]
	ds_read_b128 v[176:179], v88 offset:34240
	v_mfma_f32_16x16x32_bf16 v[2:5], v[184:187], v[14:17], v[2:5]
	ds_read_b128 v[184:187], v200 offset:1216
	s_waitcnt vmcnt(48)
	v_cndmask_b32_e64 v192, v51, v50, vcc
	v_cndmask_b32_e64 v193, v53, v52, vcc
	v_cndmask_b32_e64 v194, v55, v54, vcc
	v_cndmask_b32_e64 v195, v57, v56, vcc
	v_mov_b32_dpp v196, v192 quad_perm:[1,0,3,2] row_mask:0xf bank_mask:0xf
	v_mov_b32_dpp v197, v193 quad_perm:[1,0,3,2] row_mask:0xf bank_mask:0xf
	v_mov_b32_dpp v198, v194 quad_perm:[1,0,3,2] row_mask:0xf bank_mask:0xf
	v_mov_b32_dpp v199, v195 quad_perm:[1,0,3,2] row_mask:0xf bank_mask:0xf
	v_cndmask_b32_e64 v50, v50, v196, vcc
	v_cndmask_b32_e64 v51, v196, v51, vcc
	v_cndmask_b32_e64 v52, v52, v197, vcc
	v_cndmask_b32_e64 v53, v197, v53, vcc
	v_cndmask_b32_e64 v54, v54, v198, vcc
	v_cndmask_b32_e64 v55, v198, v55, vcc
	v_cndmask_b32_e64 v56, v56, v199, vcc
	v_cndmask_b32_e64 v57, v199, v57, vcc
	v_cvt_pk_bf16_f32 v14, v50, v51
	v_cvt_pk_bf16_f32 v15, v52, v53
	v_cvt_pk_bf16_f32 v16, v54, v55
	v_cvt_pk_bf16_f32 v17, v56, v57
	v_lshlrev_b32_e32 v84, 16, v14
	v_and_b32_e32 v85, 0xffff0000, v14
	v_sub_f32_e32 v50, v50, v84
	v_sub_f32_e32 v51, v51, v85
	v_cvt_pk_bf16_f32 v188, v50, v51
	v_lshlrev_b32_e32 v84, 16, v15
	v_and_b32_e32 v85, 0xffff0000, v15
	v_sub_f32_e32 v52, v52, v84
	v_sub_f32_e32 v53, v53, v85
	v_cvt_pk_bf16_f32 v189, v52, v53
	v_lshlrev_b32_e32 v84, 16, v16
	v_and_b32_e32 v85, 0xffff0000, v16
	v_sub_f32_e32 v54, v54, v84
	v_sub_f32_e32 v55, v55, v85
	v_cvt_pk_bf16_f32 v190, v54, v55
	v_lshlrev_b32_e32 v84, 16, v17
	v_and_b32_e32 v85, 0xffff0000, v17
	v_sub_f32_e32 v56, v56, v84
	v_sub_f32_e32 v57, v57, v85
	v_cvt_pk_bf16_f32 v191, v56, v57
	s_waitcnt lgkmcnt(0)
	v_mfma_f32_16x16x32_bf16 v[10:13], v[164:167], v[14:17], v[10:13]
	v_mfma_f32_16x16x32_bf16 v[6:9], v[172:175], v[14:17], v[6:9]
	v_mfma_f32_16x16x32_bf16 v[2:5], v[180:183], v[14:17], v[2:5]
	v_mfma_f32_16x16x32_bf16 v[10:13], v[164:167], v[188:191], v[10:13]
	ds_read_b128 v[164:167], v87 offset:1280
	v_mfma_f32_16x16x32_bf16 v[6:9], v[172:175], v[188:191], v[6:9]
	ds_read_b128 v[172:175], v87 offset:34304
	v_mfma_f32_16x16x32_bf16 v[2:5], v[180:183], v[188:191], v[2:5]
	ds_read_b128 v[180:183], v89 offset:1280
	v_mfma_f32_16x16x32_bf16 v[10:13], v[168:171], v[14:17], v[10:13]
	ds_read_b128 v[168:171], v88 offset:1280
	v_mfma_f32_16x16x32_bf16 v[6:9], v[176:179], v[14:17], v[6:9]
	ds_read_b128 v[176:179], v88 offset:34304
	v_mfma_f32_16x16x32_bf16 v[2:5], v[184:187], v[14:17], v[2:5]
	ds_read_b128 v[184:187], v200 offset:1280
	s_waitcnt vmcnt(44)
	v_cndmask_b32_e64 v192, v59, v58, vcc
	v_cndmask_b32_e64 v193, v61, v60, vcc
	v_cndmask_b32_e64 v194, v63, v62, vcc
	v_cndmask_b32_e64 v195, v65, v64, vcc
	v_mov_b32_dpp v196, v192 quad_perm:[1,0,3,2] row_mask:0xf bank_mask:0xf
	v_mov_b32_dpp v197, v193 quad_perm:[1,0,3,2] row_mask:0xf bank_mask:0xf
	v_mov_b32_dpp v198, v194 quad_perm:[1,0,3,2] row_mask:0xf bank_mask:0xf
	v_mov_b32_dpp v199, v195 quad_perm:[1,0,3,2] row_mask:0xf bank_mask:0xf
	v_cndmask_b32_e64 v58, v58, v196, vcc
	v_cndmask_b32_e64 v59, v196, v59, vcc
	v_cndmask_b32_e64 v60, v60, v197, vcc
	v_cndmask_b32_e64 v61, v197, v61, vcc
	v_cndmask_b32_e64 v62, v62, v198, vcc
	v_cndmask_b32_e64 v63, v198, v63, vcc
	v_cndmask_b32_e64 v64, v64, v199, vcc
	v_cndmask_b32_e64 v65, v199, v65, vcc
	v_cvt_pk_bf16_f32 v14, v58, v59
	v_cvt_pk_bf16_f32 v15, v60, v61
	v_cvt_pk_bf16_f32 v16, v62, v63
	v_cvt_pk_bf16_f32 v17, v64, v65
	v_lshlrev_b32_e32 v84, 16, v14
	v_and_b32_e32 v85, 0xffff0000, v14
	v_sub_f32_e32 v58, v58, v84
	v_sub_f32_e32 v59, v59, v85
	v_cvt_pk_bf16_f32 v188, v58, v59
	v_lshlrev_b32_e32 v84, 16, v15
	v_and_b32_e32 v85, 0xffff0000, v15
	v_sub_f32_e32 v60, v60, v84
	v_sub_f32_e32 v61, v61, v85
	v_cvt_pk_bf16_f32 v189, v60, v61
	v_lshlrev_b32_e32 v84, 16, v16
	v_and_b32_e32 v85, 0xffff0000, v16
	v_sub_f32_e32 v62, v62, v84
	v_sub_f32_e32 v63, v63, v85
	v_cvt_pk_bf16_f32 v190, v62, v63
	v_lshlrev_b32_e32 v84, 16, v17
	v_and_b32_e32 v85, 0xffff0000, v17
	v_sub_f32_e32 v64, v64, v84
	v_sub_f32_e32 v65, v65, v85
	v_cvt_pk_bf16_f32 v191, v64, v65
	s_waitcnt lgkmcnt(0)
	v_mfma_f32_16x16x32_bf16 v[10:13], v[164:167], v[14:17], v[10:13]
	v_mfma_f32_16x16x32_bf16 v[6:9], v[172:175], v[14:17], v[6:9]
	v_mfma_f32_16x16x32_bf16 v[2:5], v[180:183], v[14:17], v[2:5]
	v_mfma_f32_16x16x32_bf16 v[10:13], v[164:167], v[188:191], v[10:13]
	ds_read_b128 v[164:167], v87 offset:1344
	v_mfma_f32_16x16x32_bf16 v[6:9], v[172:175], v[188:191], v[6:9]
	ds_read_b128 v[172:175], v87 offset:34368
	v_mfma_f32_16x16x32_bf16 v[2:5], v[180:183], v[188:191], v[2:5]
	ds_read_b128 v[180:183], v89 offset:1344
	v_mfma_f32_16x16x32_bf16 v[10:13], v[168:171], v[14:17], v[10:13]
	ds_read_b128 v[168:171], v88 offset:1344
	v_mfma_f32_16x16x32_bf16 v[6:9], v[176:179], v[14:17], v[6:9]
	ds_read_b128 v[176:179], v88 offset:34368
	v_mfma_f32_16x16x32_bf16 v[2:5], v[184:187], v[14:17], v[2:5]
	ds_read_b128 v[184:187], v200 offset:1344
	s_waitcnt vmcnt(40)
	v_cndmask_b32_e64 v192, v67, v66, vcc
	v_cndmask_b32_e64 v193, v69, v68, vcc
	v_cndmask_b32_e64 v194, v71, v70, vcc
	v_cndmask_b32_e64 v195, v73, v72, vcc
	v_mov_b32_dpp v196, v192 quad_perm:[1,0,3,2] row_mask:0xf bank_mask:0xf
	v_mov_b32_dpp v197, v193 quad_perm:[1,0,3,2] row_mask:0xf bank_mask:0xf
	v_mov_b32_dpp v198, v194 quad_perm:[1,0,3,2] row_mask:0xf bank_mask:0xf
	v_mov_b32_dpp v199, v195 quad_perm:[1,0,3,2] row_mask:0xf bank_mask:0xf
	v_cndmask_b32_e64 v66, v66, v196, vcc
	v_cndmask_b32_e64 v67, v196, v67, vcc
	v_cndmask_b32_e64 v68, v68, v197, vcc
	v_cndmask_b32_e64 v69, v197, v69, vcc
	v_cndmask_b32_e64 v70, v70, v198, vcc
	v_cndmask_b32_e64 v71, v198, v71, vcc
	v_cndmask_b32_e64 v72, v72, v199, vcc
	v_cndmask_b32_e64 v73, v199, v73, vcc
	v_cvt_pk_bf16_f32 v14, v66, v67
	v_cvt_pk_bf16_f32 v15, v68, v69
	v_cvt_pk_bf16_f32 v16, v70, v71
	v_cvt_pk_bf16_f32 v17, v72, v73
	v_lshlrev_b32_e32 v84, 16, v14
	v_and_b32_e32 v85, 0xffff0000, v14
	v_sub_f32_e32 v66, v66, v84
	v_sub_f32_e32 v67, v67, v85
	v_cvt_pk_bf16_f32 v188, v66, v67
	v_lshlrev_b32_e32 v84, 16, v15
	v_and_b32_e32 v85, 0xffff0000, v15
	v_sub_f32_e32 v68, v68, v84
	v_sub_f32_e32 v69, v69, v85
	v_cvt_pk_bf16_f32 v189, v68, v69
	v_lshlrev_b32_e32 v84, 16, v16
	v_and_b32_e32 v85, 0xffff0000, v16
	v_sub_f32_e32 v70, v70, v84
	v_sub_f32_e32 v71, v71, v85
	v_cvt_pk_bf16_f32 v190, v70, v71
	v_lshlrev_b32_e32 v84, 16, v17
	v_and_b32_e32 v85, 0xffff0000, v17
	v_sub_f32_e32 v72, v72, v84
	v_sub_f32_e32 v73, v73, v85
	v_cvt_pk_bf16_f32 v191, v72, v73
	s_waitcnt lgkmcnt(0)
	v_mfma_f32_16x16x32_bf16 v[10:13], v[164:167], v[14:17], v[10:13]
	v_mfma_f32_16x16x32_bf16 v[6:9], v[172:175], v[14:17], v[6:9]
	v_mfma_f32_16x16x32_bf16 v[2:5], v[180:183], v[14:17], v[2:5]
	v_mfma_f32_16x16x32_bf16 v[10:13], v[164:167], v[188:191], v[10:13]
	ds_read_b128 v[164:167], v87 offset:1408
	v_mfma_f32_16x16x32_bf16 v[6:9], v[172:175], v[188:191], v[6:9]
	ds_read_b128 v[172:175], v87 offset:34432
	v_mfma_f32_16x16x32_bf16 v[2:5], v[180:183], v[188:191], v[2:5]
	ds_read_b128 v[180:183], v89 offset:1408
	v_mfma_f32_16x16x32_bf16 v[10:13], v[168:171], v[14:17], v[10:13]
	ds_read_b128 v[168:171], v88 offset:1408
	v_mfma_f32_16x16x32_bf16 v[6:9], v[176:179], v[14:17], v[6:9]
	ds_read_b128 v[176:179], v88 offset:34432
	v_mfma_f32_16x16x32_bf16 v[2:5], v[184:187], v[14:17], v[2:5]
	ds_read_b128 v[184:187], v200 offset:1408
	s_waitcnt vmcnt(36)
	v_cndmask_b32_e64 v192, v75, v74, vcc
	v_cndmask_b32_e64 v193, v77, v76, vcc
	v_cndmask_b32_e64 v194, v79, v78, vcc
	v_cndmask_b32_e64 v195, v81, v80, vcc
	v_mov_b32_dpp v196, v192 quad_perm:[1,0,3,2] row_mask:0xf bank_mask:0xf
	v_mov_b32_dpp v197, v193 quad_perm:[1,0,3,2] row_mask:0xf bank_mask:0xf
	v_mov_b32_dpp v198, v194 quad_perm:[1,0,3,2] row_mask:0xf bank_mask:0xf
	v_mov_b32_dpp v199, v195 quad_perm:[1,0,3,2] row_mask:0xf bank_mask:0xf
	v_cndmask_b32_e64 v74, v74, v196, vcc
	v_cndmask_b32_e64 v75, v196, v75, vcc
	v_cndmask_b32_e64 v76, v76, v197, vcc
	v_cndmask_b32_e64 v77, v197, v77, vcc
	v_cndmask_b32_e64 v78, v78, v198, vcc
	v_cndmask_b32_e64 v79, v198, v79, vcc
	v_cndmask_b32_e64 v80, v80, v199, vcc
	v_cndmask_b32_e64 v81, v199, v81, vcc
	v_cvt_pk_bf16_f32 v14, v74, v75
	v_cvt_pk_bf16_f32 v15, v76, v77
	v_cvt_pk_bf16_f32 v16, v78, v79
	v_cvt_pk_bf16_f32 v17, v80, v81
	v_lshlrev_b32_e32 v84, 16, v14
	v_and_b32_e32 v85, 0xffff0000, v14
	v_sub_f32_e32 v74, v74, v84
	v_sub_f32_e32 v75, v75, v85
	v_cvt_pk_bf16_f32 v188, v74, v75
	v_lshlrev_b32_e32 v84, 16, v15
	v_and_b32_e32 v85, 0xffff0000, v15
	v_sub_f32_e32 v76, v76, v84
	v_sub_f32_e32 v77, v77, v85
	v_cvt_pk_bf16_f32 v189, v76, v77
	v_lshlrev_b32_e32 v84, 16, v16
	v_and_b32_e32 v85, 0xffff0000, v16
	v_sub_f32_e32 v78, v78, v84
	v_sub_f32_e32 v79, v79, v85
	v_cvt_pk_bf16_f32 v190, v78, v79
	v_lshlrev_b32_e32 v84, 16, v17
	v_and_b32_e32 v85, 0xffff0000, v17
	v_sub_f32_e32 v80, v80, v84
	v_sub_f32_e32 v81, v81, v85
	v_cvt_pk_bf16_f32 v191, v80, v81
	s_waitcnt lgkmcnt(0)
	v_mfma_f32_16x16x32_bf16 v[10:13], v[164:167], v[14:17], v[10:13]
	v_mfma_f32_16x16x32_bf16 v[6:9], v[172:175], v[14:17], v[6:9]
	v_mfma_f32_16x16x32_bf16 v[2:5], v[180:183], v[14:17], v[2:5]
	v_mfma_f32_16x16x32_bf16 v[10:13], v[164:167], v[188:191], v[10:13]
	ds_read_b128 v[164:167], v87 offset:1472
	v_mfma_f32_16x16x32_bf16 v[6:9], v[172:175], v[188:191], v[6:9]
	ds_read_b128 v[172:175], v87 offset:34496
	v_mfma_f32_16x16x32_bf16 v[2:5], v[180:183], v[188:191], v[2:5]
	ds_read_b128 v[180:183], v89 offset:1472
	v_mfma_f32_16x16x32_bf16 v[10:13], v[168:171], v[14:17], v[10:13]
	ds_read_b128 v[168:171], v88 offset:1472
	v_mfma_f32_16x16x32_bf16 v[6:9], v[176:179], v[14:17], v[6:9]
	ds_read_b128 v[176:179], v88 offset:34496
	v_mfma_f32_16x16x32_bf16 v[2:5], v[184:187], v[14:17], v[2:5]
	ds_read_b128 v[184:187], v200 offset:1472
	s_waitcnt vmcnt(32)
	v_cndmask_b32_e64 v192, v93, v92, vcc
	v_cndmask_b32_e64 v193, v95, v94, vcc
	v_cndmask_b32_e64 v194, v97, v96, vcc
	v_cndmask_b32_e64 v195, v99, v98, vcc
	v_mov_b32_dpp v196, v192 quad_perm:[1,0,3,2] row_mask:0xf bank_mask:0xf
	v_mov_b32_dpp v197, v193 quad_perm:[1,0,3,2] row_mask:0xf bank_mask:0xf
	v_mov_b32_dpp v198, v194 quad_perm:[1,0,3,2] row_mask:0xf bank_mask:0xf
	v_mov_b32_dpp v199, v195 quad_perm:[1,0,3,2] row_mask:0xf bank_mask:0xf
	v_cndmask_b32_e64 v92, v92, v196, vcc
	v_cndmask_b32_e64 v93, v196, v93, vcc
	v_cndmask_b32_e64 v94, v94, v197, vcc
	v_cndmask_b32_e64 v95, v197, v95, vcc
	v_cndmask_b32_e64 v96, v96, v198, vcc
	v_cndmask_b32_e64 v97, v198, v97, vcc
	v_cndmask_b32_e64 v98, v98, v199, vcc
	v_cndmask_b32_e64 v99, v199, v99, vcc
	v_cvt_pk_bf16_f32 v14, v92, v93
	v_cvt_pk_bf16_f32 v15, v94, v95
	v_cvt_pk_bf16_f32 v16, v96, v97
	v_cvt_pk_bf16_f32 v17, v98, v99
	v_lshlrev_b32_e32 v84, 16, v14
	v_and_b32_e32 v85, 0xffff0000, v14
	v_sub_f32_e32 v92, v92, v84
	v_sub_f32_e32 v93, v93, v85
	v_cvt_pk_bf16_f32 v188, v92, v93
	v_lshlrev_b32_e32 v84, 16, v15
	v_and_b32_e32 v85, 0xffff0000, v15
	v_sub_f32_e32 v94, v94, v84
	v_sub_f32_e32 v95, v95, v85
	v_cvt_pk_bf16_f32 v189, v94, v95
	v_lshlrev_b32_e32 v84, 16, v16
	v_and_b32_e32 v85, 0xffff0000, v16
	v_sub_f32_e32 v96, v96, v84
	v_sub_f32_e32 v97, v97, v85
	v_cvt_pk_bf16_f32 v190, v96, v97
	v_lshlrev_b32_e32 v84, 16, v17
	v_and_b32_e32 v85, 0xffff0000, v17
	v_sub_f32_e32 v98, v98, v84
	v_sub_f32_e32 v99, v99, v85
	v_cvt_pk_bf16_f32 v191, v98, v99
	s_waitcnt lgkmcnt(0)
	v_mfma_f32_16x16x32_bf16 v[10:13], v[164:167], v[14:17], v[10:13]
	v_mfma_f32_16x16x32_bf16 v[6:9], v[172:175], v[14:17], v[6:9]
	v_mfma_f32_16x16x32_bf16 v[2:5], v[180:183], v[14:17], v[2:5]
	v_mfma_f32_16x16x32_bf16 v[10:13], v[164:167], v[188:191], v[10:13]
	ds_read_b128 v[164:167], v87 offset:1536
	v_mfma_f32_16x16x32_bf16 v[6:9], v[172:175], v[188:191], v[6:9]
	ds_read_b128 v[172:175], v87 offset:34560
	v_mfma_f32_16x16x32_bf16 v[2:5], v[180:183], v[188:191], v[2:5]
	ds_read_b128 v[180:183], v89 offset:1536
	v_mfma_f32_16x16x32_bf16 v[10:13], v[168:171], v[14:17], v[10:13]
	ds_read_b128 v[168:171], v88 offset:1536
	v_mfma_f32_16x16x32_bf16 v[6:9], v[176:179], v[14:17], v[6:9]
	ds_read_b128 v[176:179], v88 offset:34560
	v_mfma_f32_16x16x32_bf16 v[2:5], v[184:187], v[14:17], v[2:5]
	ds_read_b128 v[184:187], v200 offset:1536
	s_waitcnt vmcnt(28)
	v_cndmask_b32_e64 v192, v101, v100, vcc
	v_cndmask_b32_e64 v193, v103, v102, vcc
	v_cndmask_b32_e64 v194, v105, v104, vcc
	v_cndmask_b32_e64 v195, v107, v106, vcc
	v_mov_b32_dpp v196, v192 quad_perm:[1,0,3,2] row_mask:0xf bank_mask:0xf
	v_mov_b32_dpp v197, v193 quad_perm:[1,0,3,2] row_mask:0xf bank_mask:0xf
	v_mov_b32_dpp v198, v194 quad_perm:[1,0,3,2] row_mask:0xf bank_mask:0xf
	v_mov_b32_dpp v199, v195 quad_perm:[1,0,3,2] row_mask:0xf bank_mask:0xf
	v_cndmask_b32_e64 v100, v100, v196, vcc
	v_cndmask_b32_e64 v101, v196, v101, vcc
	v_cndmask_b32_e64 v102, v102, v197, vcc
	v_cndmask_b32_e64 v103, v197, v103, vcc
	v_cndmask_b32_e64 v104, v104, v198, vcc
	v_cndmask_b32_e64 v105, v198, v105, vcc
	v_cndmask_b32_e64 v106, v106, v199, vcc
	v_cndmask_b32_e64 v107, v199, v107, vcc
	v_cvt_pk_bf16_f32 v14, v100, v101
	v_cvt_pk_bf16_f32 v15, v102, v103
	v_cvt_pk_bf16_f32 v16, v104, v105
	v_cvt_pk_bf16_f32 v17, v106, v107
	v_lshlrev_b32_e32 v84, 16, v14
	v_and_b32_e32 v85, 0xffff0000, v14
	v_sub_f32_e32 v100, v100, v84
	v_sub_f32_e32 v101, v101, v85
	v_cvt_pk_bf16_f32 v188, v100, v101
	v_lshlrev_b32_e32 v84, 16, v15
	v_and_b32_e32 v85, 0xffff0000, v15
	v_sub_f32_e32 v102, v102, v84
	v_sub_f32_e32 v103, v103, v85
	v_cvt_pk_bf16_f32 v189, v102, v103
	v_lshlrev_b32_e32 v84, 16, v16
	v_and_b32_e32 v85, 0xffff0000, v16
	v_sub_f32_e32 v104, v104, v84
	v_sub_f32_e32 v105, v105, v85
	v_cvt_pk_bf16_f32 v190, v104, v105
	v_lshlrev_b32_e32 v84, 16, v17
	v_and_b32_e32 v85, 0xffff0000, v17
	v_sub_f32_e32 v106, v106, v84
	v_sub_f32_e32 v107, v107, v85
	v_cvt_pk_bf16_f32 v191, v106, v107
	s_waitcnt lgkmcnt(0)
	v_mfma_f32_16x16x32_bf16 v[10:13], v[164:167], v[14:17], v[10:13]
	v_mfma_f32_16x16x32_bf16 v[6:9], v[172:175], v[14:17], v[6:9]
	v_mfma_f32_16x16x32_bf16 v[2:5], v[180:183], v[14:17], v[2:5]
	v_mfma_f32_16x16x32_bf16 v[10:13], v[164:167], v[188:191], v[10:13]
	ds_read_b128 v[164:167], v87 offset:1600
	v_mfma_f32_16x16x32_bf16 v[6:9], v[172:175], v[188:191], v[6:9]
	ds_read_b128 v[172:175], v87 offset:34624
	v_mfma_f32_16x16x32_bf16 v[2:5], v[180:183], v[188:191], v[2:5]
	ds_read_b128 v[180:183], v89 offset:1600
	v_mfma_f32_16x16x32_bf16 v[10:13], v[168:171], v[14:17], v[10:13]
	ds_read_b128 v[168:171], v88 offset:1600
	v_mfma_f32_16x16x32_bf16 v[6:9], v[176:179], v[14:17], v[6:9]
	ds_read_b128 v[176:179], v88 offset:34624
	v_mfma_f32_16x16x32_bf16 v[2:5], v[184:187], v[14:17], v[2:5]
	ds_read_b128 v[184:187], v200 offset:1600
	s_waitcnt vmcnt(24)
	v_cndmask_b32_e64 v192, v109, v108, vcc
	v_cndmask_b32_e64 v193, v111, v110, vcc
	v_cndmask_b32_e64 v194, v113, v112, vcc
	v_cndmask_b32_e64 v195, v115, v114, vcc
	v_mov_b32_dpp v196, v192 quad_perm:[1,0,3,2] row_mask:0xf bank_mask:0xf
	v_mov_b32_dpp v197, v193 quad_perm:[1,0,3,2] row_mask:0xf bank_mask:0xf
	v_mov_b32_dpp v198, v194 quad_perm:[1,0,3,2] row_mask:0xf bank_mask:0xf
	v_mov_b32_dpp v199, v195 quad_perm:[1,0,3,2] row_mask:0xf bank_mask:0xf
	v_cndmask_b32_e64 v108, v108, v196, vcc
	v_cndmask_b32_e64 v109, v196, v109, vcc
	v_cndmask_b32_e64 v110, v110, v197, vcc
	v_cndmask_b32_e64 v111, v197, v111, vcc
	v_cndmask_b32_e64 v112, v112, v198, vcc
	v_cndmask_b32_e64 v113, v198, v113, vcc
	v_cndmask_b32_e64 v114, v114, v199, vcc
	v_cndmask_b32_e64 v115, v199, v115, vcc
	v_cvt_pk_bf16_f32 v14, v108, v109
	v_cvt_pk_bf16_f32 v15, v110, v111
	v_cvt_pk_bf16_f32 v16, v112, v113
	v_cvt_pk_bf16_f32 v17, v114, v115
	v_lshlrev_b32_e32 v84, 16, v14
	v_and_b32_e32 v85, 0xffff0000, v14
	v_sub_f32_e32 v108, v108, v84
	v_sub_f32_e32 v109, v109, v85
	v_cvt_pk_bf16_f32 v188, v108, v109
	v_lshlrev_b32_e32 v84, 16, v15
	v_and_b32_e32 v85, 0xffff0000, v15
	v_sub_f32_e32 v110, v110, v84
	v_sub_f32_e32 v111, v111, v85
	v_cvt_pk_bf16_f32 v189, v110, v111
	v_lshlrev_b32_e32 v84, 16, v16
	v_and_b32_e32 v85, 0xffff0000, v16
	v_sub_f32_e32 v112, v112, v84
	v_sub_f32_e32 v113, v113, v85
	v_cvt_pk_bf16_f32 v190, v112, v113
	v_lshlrev_b32_e32 v84, 16, v17
	v_and_b32_e32 v85, 0xffff0000, v17
	v_sub_f32_e32 v114, v114, v84
	v_sub_f32_e32 v115, v115, v85
	v_cvt_pk_bf16_f32 v191, v114, v115
	s_waitcnt lgkmcnt(0)
	v_mfma_f32_16x16x32_bf16 v[10:13], v[164:167], v[14:17], v[10:13]
	v_mfma_f32_16x16x32_bf16 v[6:9], v[172:175], v[14:17], v[6:9]
	v_mfma_f32_16x16x32_bf16 v[2:5], v[180:183], v[14:17], v[2:5]
	v_mfma_f32_16x16x32_bf16 v[10:13], v[164:167], v[188:191], v[10:13]
	ds_read_b128 v[164:167], v87 offset:1664
	v_mfma_f32_16x16x32_bf16 v[6:9], v[172:175], v[188:191], v[6:9]
	ds_read_b128 v[172:175], v87 offset:34688
	v_mfma_f32_16x16x32_bf16 v[2:5], v[180:183], v[188:191], v[2:5]
	ds_read_b128 v[180:183], v89 offset:1664
	v_mfma_f32_16x16x32_bf16 v[10:13], v[168:171], v[14:17], v[10:13]
	ds_read_b128 v[168:171], v88 offset:1664
	v_mfma_f32_16x16x32_bf16 v[6:9], v[176:179], v[14:17], v[6:9]
	ds_read_b128 v[176:179], v88 offset:34688
	v_mfma_f32_16x16x32_bf16 v[2:5], v[184:187], v[14:17], v[2:5]
	ds_read_b128 v[184:187], v200 offset:1664
	s_waitcnt vmcnt(20)
	v_cndmask_b32_e64 v192, v117, v116, vcc
	v_cndmask_b32_e64 v193, v119, v118, vcc
	v_cndmask_b32_e64 v194, v121, v120, vcc
	v_cndmask_b32_e64 v195, v123, v122, vcc
	v_mov_b32_dpp v196, v192 quad_perm:[1,0,3,2] row_mask:0xf bank_mask:0xf
	v_mov_b32_dpp v197, v193 quad_perm:[1,0,3,2] row_mask:0xf bank_mask:0xf
	v_mov_b32_dpp v198, v194 quad_perm:[1,0,3,2] row_mask:0xf bank_mask:0xf
	v_mov_b32_dpp v199, v195 quad_perm:[1,0,3,2] row_mask:0xf bank_mask:0xf
	v_cndmask_b32_e64 v116, v116, v196, vcc
	v_cndmask_b32_e64 v117, v196, v117, vcc
	v_cndmask_b32_e64 v118, v118, v197, vcc
	v_cndmask_b32_e64 v119, v197, v119, vcc
	v_cndmask_b32_e64 v120, v120, v198, vcc
	v_cndmask_b32_e64 v121, v198, v121, vcc
	v_cndmask_b32_e64 v122, v122, v199, vcc
	v_cndmask_b32_e64 v123, v199, v123, vcc
	v_cvt_pk_bf16_f32 v14, v116, v117
	v_cvt_pk_bf16_f32 v15, v118, v119
	v_cvt_pk_bf16_f32 v16, v120, v121
	v_cvt_pk_bf16_f32 v17, v122, v123
	v_lshlrev_b32_e32 v84, 16, v14
	v_and_b32_e32 v85, 0xffff0000, v14
	v_sub_f32_e32 v116, v116, v84
	v_sub_f32_e32 v117, v117, v85
	v_cvt_pk_bf16_f32 v188, v116, v117
	v_lshlrev_b32_e32 v84, 16, v15
	v_and_b32_e32 v85, 0xffff0000, v15
	v_sub_f32_e32 v118, v118, v84
	v_sub_f32_e32 v119, v119, v85
	v_cvt_pk_bf16_f32 v189, v118, v119
	v_lshlrev_b32_e32 v84, 16, v16
	v_and_b32_e32 v85, 0xffff0000, v16
	v_sub_f32_e32 v120, v120, v84
	v_sub_f32_e32 v121, v121, v85
	v_cvt_pk_bf16_f32 v190, v120, v121
	v_lshlrev_b32_e32 v84, 16, v17
	v_and_b32_e32 v85, 0xffff0000, v17
	v_sub_f32_e32 v122, v122, v84
	v_sub_f32_e32 v123, v123, v85
	v_cvt_pk_bf16_f32 v191, v122, v123
	s_waitcnt lgkmcnt(0)
	v_mfma_f32_16x16x32_bf16 v[10:13], v[164:167], v[14:17], v[10:13]
	v_mfma_f32_16x16x32_bf16 v[6:9], v[172:175], v[14:17], v[6:9]
	v_mfma_f32_16x16x32_bf16 v[2:5], v[180:183], v[14:17], v[2:5]
	v_mfma_f32_16x16x32_bf16 v[10:13], v[164:167], v[188:191], v[10:13]
	ds_read_b128 v[164:167], v87 offset:1728
	v_mfma_f32_16x16x32_bf16 v[6:9], v[172:175], v[188:191], v[6:9]
	ds_read_b128 v[172:175], v87 offset:34752
	v_mfma_f32_16x16x32_bf16 v[2:5], v[180:183], v[188:191], v[2:5]
	ds_read_b128 v[180:183], v89 offset:1728
	v_mfma_f32_16x16x32_bf16 v[10:13], v[168:171], v[14:17], v[10:13]
	ds_read_b128 v[168:171], v88 offset:1728
	v_mfma_f32_16x16x32_bf16 v[6:9], v[176:179], v[14:17], v[6:9]
	ds_read_b128 v[176:179], v88 offset:34752
	v_mfma_f32_16x16x32_bf16 v[2:5], v[184:187], v[14:17], v[2:5]
	ds_read_b128 v[184:187], v200 offset:1728
	s_waitcnt vmcnt(16)
	v_cndmask_b32_e64 v192, v125, v124, vcc
	v_cndmask_b32_e64 v193, v127, v126, vcc
	v_cndmask_b32_e64 v194, v129, v128, vcc
	v_cndmask_b32_e64 v195, v131, v130, vcc
	v_mov_b32_dpp v196, v192 quad_perm:[1,0,3,2] row_mask:0xf bank_mask:0xf
	v_mov_b32_dpp v197, v193 quad_perm:[1,0,3,2] row_mask:0xf bank_mask:0xf
	v_mov_b32_dpp v198, v194 quad_perm:[1,0,3,2] row_mask:0xf bank_mask:0xf
	v_mov_b32_dpp v199, v195 quad_perm:[1,0,3,2] row_mask:0xf bank_mask:0xf
	v_cndmask_b32_e64 v124, v124, v196, vcc
	v_cndmask_b32_e64 v125, v196, v125, vcc
	v_cndmask_b32_e64 v126, v126, v197, vcc
	v_cndmask_b32_e64 v127, v197, v127, vcc
	v_cndmask_b32_e64 v128, v128, v198, vcc
	v_cndmask_b32_e64 v129, v198, v129, vcc
	v_cndmask_b32_e64 v130, v130, v199, vcc
	v_cndmask_b32_e64 v131, v199, v131, vcc
	v_cvt_pk_bf16_f32 v14, v124, v125
	v_cvt_pk_bf16_f32 v15, v126, v127
	v_cvt_pk_bf16_f32 v16, v128, v129
	v_cvt_pk_bf16_f32 v17, v130, v131
	v_lshlrev_b32_e32 v84, 16, v14
	v_and_b32_e32 v85, 0xffff0000, v14
	v_sub_f32_e32 v124, v124, v84
	v_sub_f32_e32 v125, v125, v85
	v_cvt_pk_bf16_f32 v188, v124, v125
	v_lshlrev_b32_e32 v84, 16, v15
	v_and_b32_e32 v85, 0xffff0000, v15
	v_sub_f32_e32 v126, v126, v84
	v_sub_f32_e32 v127, v127, v85
	v_cvt_pk_bf16_f32 v189, v126, v127
	v_lshlrev_b32_e32 v84, 16, v16
	v_and_b32_e32 v85, 0xffff0000, v16
	v_sub_f32_e32 v128, v128, v84
	v_sub_f32_e32 v129, v129, v85
	v_cvt_pk_bf16_f32 v190, v128, v129
	v_lshlrev_b32_e32 v84, 16, v17
	v_and_b32_e32 v85, 0xffff0000, v17
	v_sub_f32_e32 v130, v130, v84
	v_sub_f32_e32 v131, v131, v85
	v_cvt_pk_bf16_f32 v191, v130, v131
	s_waitcnt lgkmcnt(0)
	v_mfma_f32_16x16x32_bf16 v[10:13], v[164:167], v[14:17], v[10:13]
	v_mfma_f32_16x16x32_bf16 v[6:9], v[172:175], v[14:17], v[6:9]
	v_mfma_f32_16x16x32_bf16 v[2:5], v[180:183], v[14:17], v[2:5]
	v_mfma_f32_16x16x32_bf16 v[10:13], v[164:167], v[188:191], v[10:13]
	ds_read_b128 v[164:167], v87 offset:1792
	v_mfma_f32_16x16x32_bf16 v[6:9], v[172:175], v[188:191], v[6:9]
	ds_read_b128 v[172:175], v87 offset:34816
	v_mfma_f32_16x16x32_bf16 v[2:5], v[180:183], v[188:191], v[2:5]
	ds_read_b128 v[180:183], v89 offset:1792
	v_mfma_f32_16x16x32_bf16 v[10:13], v[168:171], v[14:17], v[10:13]
	ds_read_b128 v[168:171], v88 offset:1792
	v_mfma_f32_16x16x32_bf16 v[6:9], v[176:179], v[14:17], v[6:9]
	ds_read_b128 v[176:179], v88 offset:34816
	v_mfma_f32_16x16x32_bf16 v[2:5], v[184:187], v[14:17], v[2:5]
	ds_read_b128 v[184:187], v200 offset:1792
	s_waitcnt vmcnt(12)
	v_cndmask_b32_e64 v192, v133, v132, vcc
	v_cndmask_b32_e64 v193, v135, v134, vcc
	v_cndmask_b32_e64 v194, v137, v136, vcc
	v_cndmask_b32_e64 v195, v139, v138, vcc
	v_mov_b32_dpp v196, v192 quad_perm:[1,0,3,2] row_mask:0xf bank_mask:0xf
	v_mov_b32_dpp v197, v193 quad_perm:[1,0,3,2] row_mask:0xf bank_mask:0xf
	v_mov_b32_dpp v198, v194 quad_perm:[1,0,3,2] row_mask:0xf bank_mask:0xf
	v_mov_b32_dpp v199, v195 quad_perm:[1,0,3,2] row_mask:0xf bank_mask:0xf
	v_cndmask_b32_e64 v132, v132, v196, vcc
	v_cndmask_b32_e64 v133, v196, v133, vcc
	v_cndmask_b32_e64 v134, v134, v197, vcc
	v_cndmask_b32_e64 v135, v197, v135, vcc
	v_cndmask_b32_e64 v136, v136, v198, vcc
	v_cndmask_b32_e64 v137, v198, v137, vcc
	v_cndmask_b32_e64 v138, v138, v199, vcc
	v_cndmask_b32_e64 v139, v199, v139, vcc
	v_cvt_pk_bf16_f32 v14, v132, v133
	v_cvt_pk_bf16_f32 v15, v134, v135
	v_cvt_pk_bf16_f32 v16, v136, v137
	v_cvt_pk_bf16_f32 v17, v138, v139
	v_lshlrev_b32_e32 v84, 16, v14
	v_and_b32_e32 v85, 0xffff0000, v14
	v_sub_f32_e32 v132, v132, v84
	v_sub_f32_e32 v133, v133, v85
	v_cvt_pk_bf16_f32 v188, v132, v133
	v_lshlrev_b32_e32 v84, 16, v15
	v_and_b32_e32 v85, 0xffff0000, v15
	v_sub_f32_e32 v134, v134, v84
	v_sub_f32_e32 v135, v135, v85
	v_cvt_pk_bf16_f32 v189, v134, v135
	v_lshlrev_b32_e32 v84, 16, v16
	v_and_b32_e32 v85, 0xffff0000, v16
	v_sub_f32_e32 v136, v136, v84
	v_sub_f32_e32 v137, v137, v85
	v_cvt_pk_bf16_f32 v190, v136, v137
	v_lshlrev_b32_e32 v84, 16, v17
	v_and_b32_e32 v85, 0xffff0000, v17
	v_sub_f32_e32 v138, v138, v84
	v_sub_f32_e32 v139, v139, v85
	v_cvt_pk_bf16_f32 v191, v138, v139
	s_waitcnt lgkmcnt(0)
	v_mfma_f32_16x16x32_bf16 v[10:13], v[164:167], v[14:17], v[10:13]
	v_mfma_f32_16x16x32_bf16 v[6:9], v[172:175], v[14:17], v[6:9]
	v_mfma_f32_16x16x32_bf16 v[2:5], v[180:183], v[14:17], v[2:5]
	v_mfma_f32_16x16x32_bf16 v[10:13], v[164:167], v[188:191], v[10:13]
	ds_read_b128 v[164:167], v87 offset:1856
	v_mfma_f32_16x16x32_bf16 v[6:9], v[172:175], v[188:191], v[6:9]
	ds_read_b128 v[172:175], v87 offset:34880
	v_mfma_f32_16x16x32_bf16 v[2:5], v[180:183], v[188:191], v[2:5]
	ds_read_b128 v[180:183], v89 offset:1856
	v_mfma_f32_16x16x32_bf16 v[10:13], v[168:171], v[14:17], v[10:13]
	ds_read_b128 v[168:171], v88 offset:1856
	v_mfma_f32_16x16x32_bf16 v[6:9], v[176:179], v[14:17], v[6:9]
	ds_read_b128 v[176:179], v88 offset:34880
	v_mfma_f32_16x16x32_bf16 v[2:5], v[184:187], v[14:17], v[2:5]
	ds_read_b128 v[184:187], v200 offset:1856
	s_waitcnt vmcnt(8)
	v_cndmask_b32_e64 v192, v141, v140, vcc
	v_cndmask_b32_e64 v193, v143, v142, vcc
	v_cndmask_b32_e64 v194, v145, v144, vcc
	v_cndmask_b32_e64 v195, v147, v146, vcc
	v_mov_b32_dpp v196, v192 quad_perm:[1,0,3,2] row_mask:0xf bank_mask:0xf
	v_mov_b32_dpp v197, v193 quad_perm:[1,0,3,2] row_mask:0xf bank_mask:0xf
	v_mov_b32_dpp v198, v194 quad_perm:[1,0,3,2] row_mask:0xf bank_mask:0xf
	v_mov_b32_dpp v199, v195 quad_perm:[1,0,3,2] row_mask:0xf bank_mask:0xf
	v_cndmask_b32_e64 v140, v140, v196, vcc
	v_cndmask_b32_e64 v141, v196, v141, vcc
	v_cndmask_b32_e64 v142, v142, v197, vcc
	v_cndmask_b32_e64 v143, v197, v143, vcc
	v_cndmask_b32_e64 v144, v144, v198, vcc
	v_cndmask_b32_e64 v145, v198, v145, vcc
	v_cndmask_b32_e64 v146, v146, v199, vcc
	v_cndmask_b32_e64 v147, v199, v147, vcc
	v_cvt_pk_bf16_f32 v14, v140, v141
	v_cvt_pk_bf16_f32 v15, v142, v143
	v_cvt_pk_bf16_f32 v16, v144, v145
	v_cvt_pk_bf16_f32 v17, v146, v147
	v_lshlrev_b32_e32 v84, 16, v14
	v_and_b32_e32 v85, 0xffff0000, v14
	v_sub_f32_e32 v140, v140, v84
	v_sub_f32_e32 v141, v141, v85
	v_cvt_pk_bf16_f32 v188, v140, v141
	v_lshlrev_b32_e32 v84, 16, v15
	v_and_b32_e32 v85, 0xffff0000, v15
	v_sub_f32_e32 v142, v142, v84
	v_sub_f32_e32 v143, v143, v85
	v_cvt_pk_bf16_f32 v189, v142, v143
	v_lshlrev_b32_e32 v84, 16, v16
	v_and_b32_e32 v85, 0xffff0000, v16
	v_sub_f32_e32 v144, v144, v84
	v_sub_f32_e32 v145, v145, v85
	v_cvt_pk_bf16_f32 v190, v144, v145
	v_lshlrev_b32_e32 v84, 16, v17
	v_and_b32_e32 v85, 0xffff0000, v17
	v_sub_f32_e32 v146, v146, v84
	v_sub_f32_e32 v147, v147, v85
	v_cvt_pk_bf16_f32 v191, v146, v147
	s_waitcnt lgkmcnt(0)
	v_mfma_f32_16x16x32_bf16 v[10:13], v[164:167], v[14:17], v[10:13]
	v_mfma_f32_16x16x32_bf16 v[6:9], v[172:175], v[14:17], v[6:9]
	v_mfma_f32_16x16x32_bf16 v[2:5], v[180:183], v[14:17], v[2:5]
	v_mfma_f32_16x16x32_bf16 v[10:13], v[164:167], v[188:191], v[10:13]
	ds_read_b128 v[164:167], v87 offset:1920
	v_mfma_f32_16x16x32_bf16 v[6:9], v[172:175], v[188:191], v[6:9]
	ds_read_b128 v[172:175], v87 offset:34944
	v_mfma_f32_16x16x32_bf16 v[2:5], v[180:183], v[188:191], v[2:5]
	ds_read_b128 v[180:183], v89 offset:1920
	v_mfma_f32_16x16x32_bf16 v[10:13], v[168:171], v[14:17], v[10:13]
	ds_read_b128 v[168:171], v88 offset:1920
	v_mfma_f32_16x16x32_bf16 v[6:9], v[176:179], v[14:17], v[6:9]
	ds_read_b128 v[176:179], v88 offset:34944
	v_mfma_f32_16x16x32_bf16 v[2:5], v[184:187], v[14:17], v[2:5]
	ds_read_b128 v[184:187], v200 offset:1920
	s_waitcnt vmcnt(4)
	v_cndmask_b32_e64 v192, v149, v148, vcc
	v_cndmask_b32_e64 v193, v151, v150, vcc
	v_cndmask_b32_e64 v194, v153, v152, vcc
	v_cndmask_b32_e64 v195, v155, v154, vcc
	v_mov_b32_dpp v196, v192 quad_perm:[1,0,3,2] row_mask:0xf bank_mask:0xf
	v_mov_b32_dpp v197, v193 quad_perm:[1,0,3,2] row_mask:0xf bank_mask:0xf
	v_mov_b32_dpp v198, v194 quad_perm:[1,0,3,2] row_mask:0xf bank_mask:0xf
	v_mov_b32_dpp v199, v195 quad_perm:[1,0,3,2] row_mask:0xf bank_mask:0xf
	v_cndmask_b32_e64 v148, v148, v196, vcc
	v_cndmask_b32_e64 v149, v196, v149, vcc
	v_cndmask_b32_e64 v150, v150, v197, vcc
	v_cndmask_b32_e64 v151, v197, v151, vcc
	v_cndmask_b32_e64 v152, v152, v198, vcc
	v_cndmask_b32_e64 v153, v198, v153, vcc
	v_cndmask_b32_e64 v154, v154, v199, vcc
	v_cndmask_b32_e64 v155, v199, v155, vcc
	v_cvt_pk_bf16_f32 v14, v148, v149
	v_cvt_pk_bf16_f32 v15, v150, v151
	v_cvt_pk_bf16_f32 v16, v152, v153
	v_cvt_pk_bf16_f32 v17, v154, v155
	v_lshlrev_b32_e32 v84, 16, v14
	v_and_b32_e32 v85, 0xffff0000, v14
	v_sub_f32_e32 v148, v148, v84
	v_sub_f32_e32 v149, v149, v85
	v_cvt_pk_bf16_f32 v188, v148, v149
	v_lshlrev_b32_e32 v84, 16, v15
	v_and_b32_e32 v85, 0xffff0000, v15
	v_sub_f32_e32 v150, v150, v84
	v_sub_f32_e32 v151, v151, v85
	v_cvt_pk_bf16_f32 v189, v150, v151
	v_lshlrev_b32_e32 v84, 16, v16
	v_and_b32_e32 v85, 0xffff0000, v16
	v_sub_f32_e32 v152, v152, v84
	v_sub_f32_e32 v153, v153, v85
	v_cvt_pk_bf16_f32 v190, v152, v153
	v_lshlrev_b32_e32 v84, 16, v17
	v_and_b32_e32 v85, 0xffff0000, v17
	v_sub_f32_e32 v154, v154, v84
	v_sub_f32_e32 v155, v155, v85
	v_cvt_pk_bf16_f32 v191, v154, v155
	s_waitcnt lgkmcnt(0)
	v_mfma_f32_16x16x32_bf16 v[10:13], v[164:167], v[14:17], v[10:13]
	v_mfma_f32_16x16x32_bf16 v[6:9], v[172:175], v[14:17], v[6:9]
	v_mfma_f32_16x16x32_bf16 v[2:5], v[180:183], v[14:17], v[2:5]
	v_mfma_f32_16x16x32_bf16 v[10:13], v[164:167], v[188:191], v[10:13]
	ds_read_b128 v[164:167], v87 offset:1984
	v_mfma_f32_16x16x32_bf16 v[6:9], v[172:175], v[188:191], v[6:9]
	ds_read_b128 v[172:175], v87 offset:35008
	v_mfma_f32_16x16x32_bf16 v[2:5], v[180:183], v[188:191], v[2:5]
	ds_read_b128 v[180:183], v89 offset:1984
	v_mfma_f32_16x16x32_bf16 v[10:13], v[168:171], v[14:17], v[10:13]
	ds_read_b128 v[168:171], v88 offset:1984
	v_mfma_f32_16x16x32_bf16 v[6:9], v[176:179], v[14:17], v[6:9]
	ds_read_b128 v[176:179], v88 offset:35008
	v_mfma_f32_16x16x32_bf16 v[2:5], v[184:187], v[14:17], v[2:5]
	ds_read_b128 v[184:187], v200 offset:1984
	s_waitcnt vmcnt(0)
	v_cndmask_b32_e64 v192, v157, v156, vcc
	v_cndmask_b32_e64 v193, v159, v158, vcc
	v_cndmask_b32_e64 v194, v161, v160, vcc
	v_cndmask_b32_e64 v195, v163, v162, vcc
	v_mov_b32_dpp v196, v192 quad_perm:[1,0,3,2] row_mask:0xf bank_mask:0xf
	v_mov_b32_dpp v197, v193 quad_perm:[1,0,3,2] row_mask:0xf bank_mask:0xf
	v_mov_b32_dpp v198, v194 quad_perm:[1,0,3,2] row_mask:0xf bank_mask:0xf
	v_mov_b32_dpp v199, v195 quad_perm:[1,0,3,2] row_mask:0xf bank_mask:0xf
	v_cndmask_b32_e64 v156, v156, v196, vcc
	v_cndmask_b32_e64 v157, v196, v157, vcc
	v_cndmask_b32_e64 v158, v158, v197, vcc
	v_cndmask_b32_e64 v159, v197, v159, vcc
	v_cndmask_b32_e64 v160, v160, v198, vcc
	v_cndmask_b32_e64 v161, v198, v161, vcc
	v_cndmask_b32_e64 v162, v162, v199, vcc
	v_cndmask_b32_e64 v163, v199, v163, vcc
	v_cvt_pk_bf16_f32 v14, v156, v157
	v_cvt_pk_bf16_f32 v15, v158, v159
	v_cvt_pk_bf16_f32 v16, v160, v161
	v_cvt_pk_bf16_f32 v17, v162, v163
	v_lshlrev_b32_e32 v84, 16, v14
	v_and_b32_e32 v85, 0xffff0000, v14
	v_sub_f32_e32 v156, v156, v84
	v_sub_f32_e32 v157, v157, v85
	v_cvt_pk_bf16_f32 v188, v156, v157
	v_lshlrev_b32_e32 v84, 16, v15
	v_and_b32_e32 v85, 0xffff0000, v15
	v_sub_f32_e32 v158, v158, v84
	v_sub_f32_e32 v159, v159, v85
	v_cvt_pk_bf16_f32 v189, v158, v159
	v_lshlrev_b32_e32 v84, 16, v16
	v_and_b32_e32 v85, 0xffff0000, v16
	v_sub_f32_e32 v160, v160, v84
	v_sub_f32_e32 v161, v161, v85
	v_cvt_pk_bf16_f32 v190, v160, v161
	v_lshlrev_b32_e32 v84, 16, v17
	v_and_b32_e32 v85, 0xffff0000, v17
	v_sub_f32_e32 v162, v162, v84
	v_sub_f32_e32 v163, v163, v85
	v_cvt_pk_bf16_f32 v191, v162, v163
	s_waitcnt lgkmcnt(0)
	v_mfma_f32_16x16x32_bf16 v[10:13], v[164:167], v[14:17], v[10:13]
	v_mfma_f32_16x16x32_bf16 v[6:9], v[172:175], v[14:17], v[6:9]
	v_mfma_f32_16x16x32_bf16 v[2:5], v[180:183], v[14:17], v[2:5]
	v_mfma_f32_16x16x32_bf16 v[10:13], v[164:167], v[188:191], v[10:13]
	v_mfma_f32_16x16x32_bf16 v[6:9], v[172:175], v[188:191], v[6:9]
	v_mfma_f32_16x16x32_bf16 v[2:5], v[180:183], v[188:191], v[2:5]
	v_mfma_f32_16x16x32_bf16 v[10:13], v[168:171], v[14:17], v[10:13]
	v_mfma_f32_16x16x32_bf16 v[6:9], v[176:179], v[14:17], v[6:9]
	v_mfma_f32_16x16x32_bf16 v[2:5], v[184:187], v[14:17], v[2:5]
	s_nop 7
	s_nop 3
	v_lshlrev_b32_e32 v82, 2, v18
	v_lshlrev_b32_e32 v16, 2, v19
	v_cmp_gt_i32_e32 vcc, 9, v19
	v_lshl_add_u64 v[14:15], s[38:39], 0, v[82:83]
	s_and_saveexec_b64 s[4:5], vcc
	s_cbranch_execz .LBB0_136
	v_mad_i64_i32 v[20:21], s[6:7], v16, s62, 0
	v_add_f32_e32 v10, 0, v10
	v_lshl_add_u64 v[20:21], v[20:21], 2, v[14:15]
	global_store_dword v[20:21], v10, off
